# wide 16-byte epilogue stores via permlane merge in FFN-in, in-proj, QKV GEMM epilogues and kv-state tiles; hand-written QKV epilogue
# speedup vs baseline: 1.1371x; 1.0351x over previous
.LBB0_46:
	s_or_b64 exec, exec, s[6:7]
	v_add_u32_e32 v128, s4, v143
	v_lshlrev_b32_e32 v129, 6, v142
	v_lshl_or_b32 v129, v141, 4, v129
	s_lshl_b32 s0, s16, 8
	v_add_u32_e32 v129, s0, v129
	s_movk_i32 s1, 0x1600
	v_mad_u32_u24 v130, v128, s1, v129
	s_mov_b32 s2, 0xbfb8aa3b
	s_mov_b32 s3, 0xbfb8aa3b
	s_mov_b32 s28, 1.0
	s_mov_b32 s29, 1.0
	v_mov_b32_e32 v131, v130
	v_pk_mul_f32 v[132:133], v[120:121], s[2:3]
	v_pk_mul_f32 v[134:135], v[122:123], s[2:3]
	v_exp_f32_e32 v132, v132
	v_exp_f32_e32 v133, v133
	v_exp_f32_e32 v134, v134
	v_exp_f32_e32 v135, v135
	v_pk_mul_f32 v[136:137], v[112:113], s[2:3]
	v_pk_mul_f32 v[138:139], v[114:115], s[2:3]
	v_exp_f32_e32 v136, v136
	v_exp_f32_e32 v137, v137
	v_exp_f32_e32 v138, v138
	v_exp_f32_e32 v139, v139
	v_pk_add_f32 v[132:133], v[132:133], s[28:29]
	v_pk_add_f32 v[134:135], v[134:135], s[28:29]
	v_rcp_f32_e32 v132, v132
	v_rcp_f32_e32 v133, v133
	v_rcp_f32_e32 v134, v134
	v_rcp_f32_e32 v135, v135
	v_pk_add_f32 v[136:137], v[136:137], s[28:29]
	v_pk_add_f32 v[138:139], v[138:139], s[28:29]
	v_rcp_f32_e32 v136, v136
	v_rcp_f32_e32 v137, v137
	v_rcp_f32_e32 v138, v138
	v_rcp_f32_e32 v139, v139
	v_pk_mul_f32 v[120:121], v[120:121], v[132:133]
	v_pk_mul_f32 v[122:123], v[122:123], v[134:135]
	v_pk_mul_f32 v[120:121], v[120:121], v[124:125]
	v_pk_mul_f32 v[122:123], v[122:123], v[126:127]
	v_cvt_pk_bf16_f32 v144, v120, v121
	v_cvt_pk_bf16_f32 v145, v122, v123
	v_pk_mul_f32 v[112:113], v[112:113], v[136:137]
	v_pk_mul_f32 v[114:115], v[114:115], v[138:139]
	v_pk_mul_f32 v[112:113], v[112:113], v[116:117]
	v_pk_mul_f32 v[114:115], v[114:115], v[118:119]
	v_cvt_pk_bf16_f32 v146, v112, v113
	v_cvt_pk_bf16_f32 v147, v114, v115
	s_nop 1
	v_permlane32_swap_b32_e32 v144, v146
	v_permlane32_swap_b32_e32 v145, v147
	s_nop 1
	v_permlane16_swap_b32_e32 v144, v146
	v_permlane16_swap_b32_e32 v145, v147
	global_store_dwordx4 v131, v[144:147], s[66:67]
	v_add_u32_e32 v131, 0x16000, v130
	v_pk_mul_f32 v[132:133], v[104:105], s[2:3]
	v_pk_mul_f32 v[134:135], v[106:107], s[2:3]
	v_exp_f32_e32 v132, v132
	v_exp_f32_e32 v133, v133
	v_exp_f32_e32 v134, v134
	v_exp_f32_e32 v135, v135
	v_pk_mul_f32 v[136:137], v[96:97], s[2:3]
	v_pk_mul_f32 v[138:139], v[98:99], s[2:3]
	v_exp_f32_e32 v136, v136
	v_exp_f32_e32 v137, v137
	v_exp_f32_e32 v138, v138
	v_exp_f32_e32 v139, v139
	v_pk_add_f32 v[132:133], v[132:133], s[28:29]
	v_pk_add_f32 v[134:135], v[134:135], s[28:29]
	v_rcp_f32_e32 v132, v132
	v_rcp_f32_e32 v133, v133
	v_rcp_f32_e32 v134, v134
	v_rcp_f32_e32 v135, v135
	v_pk_add_f32 v[136:137], v[136:137], s[28:29]
	v_pk_add_f32 v[138:139], v[138:139], s[28:29]
	v_rcp_f32_e32 v136, v136
	v_rcp_f32_e32 v137, v137
	v_rcp_f32_e32 v138, v138
	v_rcp_f32_e32 v139, v139
	v_pk_mul_f32 v[104:105], v[104:105], v[132:133]
	v_pk_mul_f32 v[106:107], v[106:107], v[134:135]
	v_pk_mul_f32 v[104:105], v[104:105], v[108:109]
	v_pk_mul_f32 v[106:107], v[106:107], v[110:111]
	v_cvt_pk_bf16_f32 v148, v104, v105
	v_cvt_pk_bf16_f32 v149, v106, v107
	v_pk_mul_f32 v[96:97], v[96:97], v[136:137]
	v_pk_mul_f32 v[98:99], v[98:99], v[138:139]
	v_pk_mul_f32 v[96:97], v[96:97], v[100:101]
	v_pk_mul_f32 v[98:99], v[98:99], v[102:103]
	v_cvt_pk_bf16_f32 v150, v96, v97
	v_cvt_pk_bf16_f32 v151, v98, v99
	s_nop 1
	v_permlane32_swap_b32_e32 v148, v150
	v_permlane32_swap_b32_e32 v149, v151
	s_nop 1
	v_permlane16_swap_b32_e32 v148, v150
	v_permlane16_swap_b32_e32 v149, v151
	global_store_dwordx4 v131, v[148:151], s[66:67]
	v_add_u32_e32 v131, 0x2c000, v130
	v_pk_mul_f32 v[132:133], v[88:89], s[2:3]
	v_pk_mul_f32 v[134:135], v[90:91], s[2:3]
	v_exp_f32_e32 v132, v132
	v_exp_f32_e32 v133, v133
	v_exp_f32_e32 v134, v134
	v_exp_f32_e32 v135, v135
	v_pk_mul_f32 v[136:137], v[80:81], s[2:3]
	v_pk_mul_f32 v[138:139], v[82:83], s[2:3]
	v_exp_f32_e32 v136, v136
	v_exp_f32_e32 v137, v137
	v_exp_f32_e32 v138, v138
	v_exp_f32_e32 v139, v139
	v_pk_add_f32 v[132:133], v[132:133], s[28:29]
	v_pk_add_f32 v[134:135], v[134:135], s[28:29]
	v_rcp_f32_e32 v132, v132
	v_rcp_f32_e32 v133, v133
	v_rcp_f32_e32 v134, v134
	v_rcp_f32_e32 v135, v135
	v_pk_add_f32 v[136:137], v[136:137], s[28:29]
	v_pk_add_f32 v[138:139], v[138:139], s[28:29]
	v_rcp_f32_e32 v136, v136
	v_rcp_f32_e32 v137, v137
	v_rcp_f32_e32 v138, v138
	v_rcp_f32_e32 v139, v139
	v_pk_mul_f32 v[88:89], v[88:89], v[132:133]
	v_pk_mul_f32 v[90:91], v[90:91], v[134:135]
	v_pk_mul_f32 v[88:89], v[88:89], v[92:93]
	v_pk_mul_f32 v[90:91], v[90:91], v[94:95]
	v_cvt_pk_bf16_f32 v144, v88, v89
	v_cvt_pk_bf16_f32 v145, v90, v91
	v_pk_mul_f32 v[80:81], v[80:81], v[136:137]
	v_pk_mul_f32 v[82:83], v[82:83], v[138:139]
	v_pk_mul_f32 v[80:81], v[80:81], v[84:85]
	v_pk_mul_f32 v[82:83], v[82:83], v[86:87]
	v_cvt_pk_bf16_f32 v146, v80, v81
	v_cvt_pk_bf16_f32 v147, v82, v83
	s_nop 1
	v_permlane32_swap_b32_e32 v144, v146
	v_permlane32_swap_b32_e32 v145, v147
	s_nop 1
	v_permlane16_swap_b32_e32 v144, v146
	v_permlane16_swap_b32_e32 v145, v147
	global_store_dwordx4 v131, v[144:147], s[66:67]
	v_add_u32_e32 v131, 0x42000, v130
	v_pk_mul_f32 v[132:133], v[72:73], s[2:3]
	v_pk_mul_f32 v[134:135], v[74:75], s[2:3]
	v_exp_f32_e32 v132, v132
	v_exp_f32_e32 v133, v133
	v_exp_f32_e32 v134, v134
	v_exp_f32_e32 v135, v135
	v_pk_mul_f32 v[136:137], v[64:65], s[2:3]
	v_pk_mul_f32 v[138:139], v[66:67], s[2:3]
	v_exp_f32_e32 v136, v136
	v_exp_f32_e32 v137, v137
	v_exp_f32_e32 v138, v138
	v_exp_f32_e32 v139, v139
	v_pk_add_f32 v[132:133], v[132:133], s[28:29]
	v_pk_add_f32 v[134:135], v[134:135], s[28:29]
	v_rcp_f32_e32 v132, v132
	v_rcp_f32_e32 v133, v133
	v_rcp_f32_e32 v134, v134
	v_rcp_f32_e32 v135, v135
	v_pk_add_f32 v[136:137], v[136:137], s[28:29]
	v_pk_add_f32 v[138:139], v[138:139], s[28:29]
	v_rcp_f32_e32 v136, v136
	v_rcp_f32_e32 v137, v137
	v_rcp_f32_e32 v138, v138
	v_rcp_f32_e32 v139, v139
	v_pk_mul_f32 v[72:73], v[72:73], v[132:133]
	v_pk_mul_f32 v[74:75], v[74:75], v[134:135]
	v_pk_mul_f32 v[72:73], v[72:73], v[76:77]
	v_pk_mul_f32 v[74:75], v[74:75], v[78:79]
	v_cvt_pk_bf16_f32 v148, v72, v73
	v_cvt_pk_bf16_f32 v149, v74, v75
	v_pk_mul_f32 v[64:65], v[64:65], v[136:137]
	v_pk_mul_f32 v[66:67], v[66:67], v[138:139]
	v_pk_mul_f32 v[64:65], v[64:65], v[68:69]
	v_pk_mul_f32 v[66:67], v[66:67], v[70:71]
	v_cvt_pk_bf16_f32 v150, v64, v65
	v_cvt_pk_bf16_f32 v151, v66, v67
	s_nop 1
	v_permlane32_swap_b32_e32 v148, v150
	v_permlane32_swap_b32_e32 v149, v151
	s_nop 1
	v_permlane16_swap_b32_e32 v148, v150
	v_permlane16_swap_b32_e32 v149, v151
	global_store_dwordx4 v131, v[148:151], s[66:67]
	v_add_u32_e32 v131, 0xb0000, v130
	v_pk_mul_f32 v[132:133], v[56:57], s[2:3]
	v_pk_mul_f32 v[134:135], v[58:59], s[2:3]
	v_exp_f32_e32 v132, v132
	v_exp_f32_e32 v133, v133
	v_exp_f32_e32 v134, v134
	v_exp_f32_e32 v135, v135
	v_pk_mul_f32 v[136:137], v[48:49], s[2:3]
	v_pk_mul_f32 v[138:139], v[50:51], s[2:3]
	v_exp_f32_e32 v136, v136
	v_exp_f32_e32 v137, v137
	v_exp_f32_e32 v138, v138
	v_exp_f32_e32 v139, v139
	v_pk_add_f32 v[132:133], v[132:133], s[28:29]
	v_pk_add_f32 v[134:135], v[134:135], s[28:29]
	v_rcp_f32_e32 v132, v132
	v_rcp_f32_e32 v133, v133
	v_rcp_f32_e32 v134, v134
	v_rcp_f32_e32 v135, v135
	v_pk_add_f32 v[136:137], v[136:137], s[28:29]
	v_pk_add_f32 v[138:139], v[138:139], s[28:29]
	v_rcp_f32_e32 v136, v136
	v_rcp_f32_e32 v137, v137
	v_rcp_f32_e32 v138, v138
	v_rcp_f32_e32 v139, v139
	v_pk_mul_f32 v[56:57], v[56:57], v[132:133]
	v_pk_mul_f32 v[58:59], v[58:59], v[134:135]
	v_pk_mul_f32 v[56:57], v[56:57], v[60:61]
	v_pk_mul_f32 v[58:59], v[58:59], v[62:63]
	v_cvt_pk_bf16_f32 v144, v56, v57
	v_cvt_pk_bf16_f32 v145, v58, v59
	v_pk_mul_f32 v[48:49], v[48:49], v[136:137]
	v_pk_mul_f32 v[50:51], v[50:51], v[138:139]
	v_pk_mul_f32 v[48:49], v[48:49], v[52:53]
	v_pk_mul_f32 v[50:51], v[50:51], v[54:55]
	v_cvt_pk_bf16_f32 v146, v48, v49
	v_cvt_pk_bf16_f32 v147, v50, v51
	s_nop 1
	v_permlane32_swap_b32_e32 v144, v146
	v_permlane32_swap_b32_e32 v145, v147
	s_nop 1
	v_permlane16_swap_b32_e32 v144, v146
	v_permlane16_swap_b32_e32 v145, v147
	global_store_dwordx4 v131, v[144:147], s[66:67]
	v_add_u32_e32 v131, 0xc6000, v130
	v_pk_mul_f32 v[132:133], v[40:41], s[2:3]
	v_pk_mul_f32 v[134:135], v[42:43], s[2:3]
	v_exp_f32_e32 v132, v132
	v_exp_f32_e32 v133, v133
	v_exp_f32_e32 v134, v134
	v_exp_f32_e32 v135, v135
	v_pk_mul_f32 v[136:137], v[32:33], s[2:3]
	v_pk_mul_f32 v[138:139], v[34:35], s[2:3]
	v_exp_f32_e32 v136, v136
	v_exp_f32_e32 v137, v137
	v_exp_f32_e32 v138, v138
	v_exp_f32_e32 v139, v139
	v_pk_add_f32 v[132:133], v[132:133], s[28:29]
	v_pk_add_f32 v[134:135], v[134:135], s[28:29]
	v_rcp_f32_e32 v132, v132
	v_rcp_f32_e32 v133, v133
	v_rcp_f32_e32 v134, v134
	v_rcp_f32_e32 v135, v135
	v_pk_add_f32 v[136:137], v[136:137], s[28:29]
	v_pk_add_f32 v[138:139], v[138:139], s[28:29]
	v_rcp_f32_e32 v136, v136
	v_rcp_f32_e32 v137, v137
	v_rcp_f32_e32 v138, v138
	v_rcp_f32_e32 v139, v139
	v_pk_mul_f32 v[40:41], v[40:41], v[132:133]
	v_pk_mul_f32 v[42:43], v[42:43], v[134:135]
	v_pk_mul_f32 v[40:41], v[40:41], v[44:45]
	v_pk_mul_f32 v[42:43], v[42:43], v[46:47]
	v_cvt_pk_bf16_f32 v148, v40, v41
	v_cvt_pk_bf16_f32 v149, v42, v43
	v_pk_mul_f32 v[32:33], v[32:33], v[136:137]
	v_pk_mul_f32 v[34:35], v[34:35], v[138:139]
	v_pk_mul_f32 v[32:33], v[32:33], v[36:37]
	v_pk_mul_f32 v[34:35], v[34:35], v[38:39]
	v_cvt_pk_bf16_f32 v150, v32, v33
	v_cvt_pk_bf16_f32 v151, v34, v35
	s_nop 1
	v_permlane32_swap_b32_e32 v148, v150
	v_permlane32_swap_b32_e32 v149, v151
	s_nop 1
	v_permlane16_swap_b32_e32 v148, v150
	v_permlane16_swap_b32_e32 v149, v151
	global_store_dwordx4 v131, v[148:151], s[66:67]
	v_add_u32_e32 v131, 0xdc000, v130
	v_pk_mul_f32 v[132:133], v[24:25], s[2:3]
	v_pk_mul_f32 v[134:135], v[26:27], s[2:3]
	v_exp_f32_e32 v132, v132
	v_exp_f32_e32 v133, v133
	v_exp_f32_e32 v134, v134
	v_exp_f32_e32 v135, v135
	v_pk_mul_f32 v[136:137], v[16:17], s[2:3]
	v_pk_mul_f32 v[138:139], v[18:19], s[2:3]
	v_exp_f32_e32 v136, v136
	v_exp_f32_e32 v137, v137
	v_exp_f32_e32 v138, v138
	v_exp_f32_e32 v139, v139
	v_pk_add_f32 v[132:133], v[132:133], s[28:29]
	v_pk_add_f32 v[134:135], v[134:135], s[28:29]
	v_rcp_f32_e32 v132, v132
	v_rcp_f32_e32 v133, v133
	v_rcp_f32_e32 v134, v134
	v_rcp_f32_e32 v135, v135
	v_pk_add_f32 v[136:137], v[136:137], s[28:29]
	v_pk_add_f32 v[138:139], v[138:139], s[28:29]
	v_rcp_f32_e32 v136, v136
	v_rcp_f32_e32 v137, v137
	v_rcp_f32_e32 v138, v138
	v_rcp_f32_e32 v139, v139
	v_pk_mul_f32 v[24:25], v[24:25], v[132:133]
	v_pk_mul_f32 v[26:27], v[26:27], v[134:135]
	v_pk_mul_f32 v[24:25], v[24:25], v[28:29]
	v_pk_mul_f32 v[26:27], v[26:27], v[30:31]
	v_cvt_pk_bf16_f32 v144, v24, v25
	v_cvt_pk_bf16_f32 v145, v26, v27
	v_pk_mul_f32 v[16:17], v[16:17], v[136:137]
	v_pk_mul_f32 v[18:19], v[18:19], v[138:139]
	v_pk_mul_f32 v[16:17], v[16:17], v[20:21]
	v_pk_mul_f32 v[18:19], v[18:19], v[22:23]
	v_cvt_pk_bf16_f32 v146, v16, v17
	v_cvt_pk_bf16_f32 v147, v18, v19
	s_nop 1
	v_permlane32_swap_b32_e32 v144, v146
	v_permlane32_swap_b32_e32 v145, v147
	s_nop 1
	v_permlane16_swap_b32_e32 v144, v146
	v_permlane16_swap_b32_e32 v145, v147
	global_store_dwordx4 v131, v[144:147], s[66:67]
	v_add_u32_e32 v131, 0xf2000, v130
	v_pk_mul_f32 v[132:133], v[8:9], s[2:3]
	v_pk_mul_f32 v[134:135], v[10:11], s[2:3]
	v_exp_f32_e32 v132, v132
	v_exp_f32_e32 v133, v133
	v_exp_f32_e32 v134, v134
	v_exp_f32_e32 v135, v135
	v_pk_mul_f32 v[136:137], v[0:1], s[2:3]
	v_pk_mul_f32 v[138:139], v[2:3], s[2:3]
	v_exp_f32_e32 v136, v136
	v_exp_f32_e32 v137, v137
	v_exp_f32_e32 v138, v138
	v_exp_f32_e32 v139, v139
	v_pk_add_f32 v[132:133], v[132:133], s[28:29]
	v_pk_add_f32 v[134:135], v[134:135], s[28:29]
	v_rcp_f32_e32 v132, v132
	v_rcp_f32_e32 v133, v133
	v_rcp_f32_e32 v134, v134
	v_rcp_f32_e32 v135, v135
	v_pk_add_f32 v[136:137], v[136:137], s[28:29]
	v_pk_add_f32 v[138:139], v[138:139], s[28:29]
	v_rcp_f32_e32 v136, v136
	v_rcp_f32_e32 v137, v137
	v_rcp_f32_e32 v138, v138
	v_rcp_f32_e32 v139, v139
	v_pk_mul_f32 v[8:9], v[8:9], v[132:133]
	v_pk_mul_f32 v[10:11], v[10:11], v[134:135]
	v_pk_mul_f32 v[8:9], v[8:9], v[12:13]
	v_pk_mul_f32 v[10:11], v[10:11], v[14:15]
	v_cvt_pk_bf16_f32 v148, v8, v9
	v_cvt_pk_bf16_f32 v149, v10, v11
	v_pk_mul_f32 v[0:1], v[0:1], v[136:137]
	v_pk_mul_f32 v[2:3], v[2:3], v[138:139]
	v_pk_mul_f32 v[0:1], v[0:1], v[4:5]
	v_pk_mul_f32 v[2:3], v[2:3], v[6:7]
	v_cvt_pk_bf16_f32 v150, v0, v1
	v_cvt_pk_bf16_f32 v151, v2, v3
	s_nop 1
	v_permlane32_swap_b32_e32 v148, v150
	v_permlane32_swap_b32_e32 v149, v151
	s_nop 1
	v_permlane16_swap_b32_e32 v148, v150
	v_permlane16_swap_b32_e32 v149, v151
	global_store_dwordx4 v131, v[148:151], s[66:67]
	s_add_i32 s13, s13, s12
	s_cmpk_gt_i32 s13, 0x57f
	s_waitcnt vmcnt(0)
	s_cbranch_scc1 .LBB0_53

.LBB0_102:
	s_andn2_b64 vcc, exec, s[4:5]
	s_cbranch_vccnz .LBB0_335
	v_readlane_b32 s0, v255, 12
	s_movk_i32 s50, 0xff80
	s_cmp_lt_i32 s0, 10
	s_mov_b64 s[4:5], -1
	s_mov_b64 s[28:29], 0x2080100
	s_mov_b64 s[30:31], 0x2130100
	s_mov_b64 s[34:35], 0x2080180
	s_mov_b64 s[36:37], 0x2130180
	s_mov_b32 s51, -1
	s_cbranch_scc1 .LBB0_172
	v_readlane_b32 s0, v255, 12
	s_cmp_gt_i32 s0, 10
	s_cbranch_scc0 .LBB0_167
	v_readlane_b32 s20, v255, 7
	s_mov_b32 s21, s43
	s_cmpk_gt_i32 s21, 0x18b
	s_cbranch_scc1 .LBB0_166
	s_load_dwordx4 s[8:11], s[54:55], 0x98
	s_add_u32 s6, s46, 0x30a4000
	s_addc_u32 s7, s47, 0
	s_add_u32 s22, s46, 0x2b80000
	s_addc_u32 s23, s47, 0
	s_branch .LBB0_109
.LBB0_109:
	s_ashr_i32 s0, s21, 31
	s_lshr_b32 s0, s0, 29
	s_add_i32 s1, s21, s0
	s_and_b32 s0, s1, -8
	s_sub_i32 s2, s21, s0
	v_mbcnt_lo_u32_b32 v0, -1, 0
	v_mbcnt_hi_u32_b32 v0, -1, v0
	s_cmp_gt_i32 s2, 3
	v_add_u32_e32 v140, s48, v0
	s_mov_b64 s[4:5], -1
	s_cbranch_scc0 .LBB0_111
	s_mul_i32 s0, s2, 49
	s_add_i32 s0, s0, 4
	s_mov_b64 s[4:5], 0

.LBB0_119:
	s_or_b64 exec, exec, s[14:15]
	s_lshr_b32 s1, s0, 24
	v_add_u32_e32 v128, s4, v142
	v_lshrrev_b32_e32 v129, 2, v140
	v_and_b32_e32 v129, 12, v129
	v_lshlrev_b32_e32 v170, 2, v129
	v_lshlrev_b32_e32 v129, 2, v129
	v_lshl_or_b32 v129, v169, 7, v129
	s_lshl_b32 s5, s12, 1
	v_add_u32_e32 v129, s5, v129
	s_movk_i32 s5, 0xc00
	v_mad_u32_u24 v131, v128, s5, v129
	s_cmp_gt_u32 s1, 4
	s_cbranch_scc1 .Lqkv_v
	s_cmp_eq_u32 s1, 4
	s_cselect_b32 s16, s10, s8
	s_cselect_b32 s17, s11, s9
	s_cselect_b32 s3, 1.0, 0x3e38aa3b
	global_load_dwordx4 v[198:201], v170, s[16:17]
	global_load_dwordx4 v[202:205], v170, s[16:17] offset:128
	global_load_dwordx4 v[206:209], v170, s[16:17] offset:64
	global_load_dwordx4 v[210:213], v170, s[16:17] offset:192
	s_mov_b32 s16, s3
	s_mov_b32 s17, s3
	s_cmp_lt_u32 s4, s39
	s_cselect_b64 s[24:25], -1, 0
	s_cbranch_scc0 .Lqkv_norope
	v_and_b32_e32 v171, 0x1fff, v128
	v_lshlrev_b32_e32 v171, 8, v171
	v_add_u32_e32 v171, v171, v170
	v_mov_b32_e32 v168, v171
	global_load_dwordx4 v[214:217], v168, s[6:7]
	global_load_dwordx4 v[218:221], v168, s[6:7] offset:128
	global_load_dwordx4 v[222:225], v168, s[6:7] offset:64
	global_load_dwordx4 v[226:229], v168, s[6:7] offset:192
	v_add_u32_e32 v168, 0x1000, v171
	global_load_dwordx4 v[232:235], v168, s[6:7]
	global_load_dwordx4 v[236:239], v168, s[6:7] offset:128
	global_load_dwordx4 v[240:243], v168, s[6:7] offset:64
	global_load_dwordx4 v[144:147], v168, s[6:7] offset:192
	s_branch .Lqkv_ss
.Lqkv_norope:
	v_mov_b32_e32 v214, 1.0
	v_mov_b32_e32 v215, 1.0
	v_mov_b32_e32 v216, 1.0
	v_mov_b32_e32 v217, 1.0
	v_mov_b32_e32 v218, 0
	v_mov_b32_e32 v219, 0
	v_mov_b32_e32 v220, 0
	v_mov_b32_e32 v221, 0
	v_mov_b32_e32 v222, 1.0
	v_mov_b32_e32 v223, 1.0
	v_mov_b32_e32 v224, 1.0
	v_mov_b32_e32 v225, 1.0
	v_mov_b32_e32 v226, 0
	v_mov_b32_e32 v227, 0
	v_mov_b32_e32 v228, 0
	v_mov_b32_e32 v229, 0
	v_mov_b32_e32 v232, 1.0
	v_mov_b32_e32 v233, 1.0
	v_mov_b32_e32 v234, 1.0
	v_mov_b32_e32 v235, 1.0
	v_mov_b32_e32 v236, 0
	v_mov_b32_e32 v237, 0
	v_mov_b32_e32 v238, 0
	v_mov_b32_e32 v239, 0
	v_mov_b32_e32 v240, 1.0
	v_mov_b32_e32 v241, 1.0
	v_mov_b32_e32 v242, 1.0
	v_mov_b32_e32 v243, 1.0
	v_mov_b32_e32 v144, 0
	v_mov_b32_e32 v145, 0
	v_mov_b32_e32 v146, 0
	v_mov_b32_e32 v147, 0
.Lqkv_ss:
	v_mul_f32_e32 v148, v116, v116
	v_mul_f32_e32 v150, v100, v100
	v_fmac_f32_e32 v148, v117, v117
	v_fmac_f32_e32 v150, v101, v101
	v_fmac_f32_e32 v148, v118, v118
	v_fmac_f32_e32 v150, v102, v102
	v_fmac_f32_e32 v148, v119, v119
	v_fmac_f32_e32 v150, v103, v103
	v_fmac_f32_e32 v148, v112, v112
	v_fmac_f32_e32 v150, v96, v96
	v_fmac_f32_e32 v148, v113, v113
	v_fmac_f32_e32 v150, v97, v97
	v_fmac_f32_e32 v148, v114, v114
	v_fmac_f32_e32 v150, v98, v98
	v_fmac_f32_e32 v148, v115, v115
	v_fmac_f32_e32 v150, v99, v99
	v_fmac_f32_e32 v148, v124, v124
	v_fmac_f32_e32 v150, v108, v108
	v_fmac_f32_e32 v148, v125, v125
	v_fmac_f32_e32 v150, v109, v109
	v_fmac_f32_e32 v148, v126, v126
	v_fmac_f32_e32 v150, v110, v110
	v_fmac_f32_e32 v148, v127, v127
	v_fmac_f32_e32 v150, v111, v111
	v_fmac_f32_e32 v148, v120, v120
	v_fmac_f32_e32 v150, v104, v104
	v_fmac_f32_e32 v148, v121, v121
	v_fmac_f32_e32 v150, v105, v105
	v_fmac_f32_e32 v148, v122, v122
	v_fmac_f32_e32 v150, v106, v106
	v_fmac_f32_e32 v148, v123, v123
	v_fmac_f32_e32 v150, v107, v107
	v_mul_f32_e32 v152, v84, v84
	v_mul_f32_e32 v154, v68, v68
	v_fmac_f32_e32 v152, v85, v85
	v_fmac_f32_e32 v154, v69, v69
	v_fmac_f32_e32 v152, v86, v86
	v_fmac_f32_e32 v154, v70, v70
	v_fmac_f32_e32 v152, v87, v87
	v_fmac_f32_e32 v154, v71, v71
	v_fmac_f32_e32 v152, v80, v80
	v_fmac_f32_e32 v154, v64, v64
	v_fmac_f32_e32 v152, v81, v81
	v_fmac_f32_e32 v154, v65, v65
	v_fmac_f32_e32 v152, v82, v82
	v_fmac_f32_e32 v154, v66, v66
	v_fmac_f32_e32 v152, v83, v83
	v_fmac_f32_e32 v154, v67, v67
	v_fmac_f32_e32 v152, v92, v92
	v_fmac_f32_e32 v154, v76, v76
	v_fmac_f32_e32 v152, v93, v93
	v_fmac_f32_e32 v154, v77, v77
	v_fmac_f32_e32 v152, v94, v94
	v_fmac_f32_e32 v154, v78, v78
	v_fmac_f32_e32 v152, v95, v95
	v_fmac_f32_e32 v154, v79, v79
	v_fmac_f32_e32 v152, v88, v88
	v_fmac_f32_e32 v154, v72, v72
	v_fmac_f32_e32 v152, v89, v89
	v_fmac_f32_e32 v154, v73, v73
	v_fmac_f32_e32 v152, v90, v90
	v_fmac_f32_e32 v154, v74, v74
	v_fmac_f32_e32 v152, v91, v91
	v_fmac_f32_e32 v154, v75, v75
	v_mul_f32_e32 v156, v60, v60
	v_mul_f32_e32 v158, v44, v44
	v_fmac_f32_e32 v156, v61, v61
	v_fmac_f32_e32 v158, v45, v45
	v_fmac_f32_e32 v156, v62, v62
	v_fmac_f32_e32 v158, v46, v46
	v_fmac_f32_e32 v156, v63, v63
	v_fmac_f32_e32 v158, v47, v47
	v_fmac_f32_e32 v156, v48, v48
	v_fmac_f32_e32 v158, v32, v32
	v_fmac_f32_e32 v156, v49, v49
	v_fmac_f32_e32 v158, v33, v33
	v_fmac_f32_e32 v156, v50, v50
	v_fmac_f32_e32 v158, v34, v34
	v_fmac_f32_e32 v156, v51, v51
	v_fmac_f32_e32 v158, v35, v35
	v_fmac_f32_e32 v156, v56, v56
	v_fmac_f32_e32 v158, v40, v40
	v_fmac_f32_e32 v156, v57, v57
	v_fmac_f32_e32 v158, v41, v41
	v_fmac_f32_e32 v156, v58, v58
	v_fmac_f32_e32 v158, v42, v42
	v_fmac_f32_e32 v156, v59, v59
	v_fmac_f32_e32 v158, v43, v43
	v_fmac_f32_e32 v156, v52, v52
	v_fmac_f32_e32 v158, v36, v36
	v_fmac_f32_e32 v156, v53, v53
	v_fmac_f32_e32 v158, v37, v37
	v_fmac_f32_e32 v156, v54, v54
	v_fmac_f32_e32 v158, v38, v38
	v_fmac_f32_e32 v156, v55, v55
	v_fmac_f32_e32 v158, v39, v39
	v_mul_f32_e32 v132, v28, v28
	v_mul_f32_e32 v134, v12, v12
	v_fmac_f32_e32 v132, v29, v29
	v_fmac_f32_e32 v134, v13, v13
	v_fmac_f32_e32 v132, v30, v30
	v_fmac_f32_e32 v134, v14, v14
	v_fmac_f32_e32 v132, v31, v31
	v_fmac_f32_e32 v134, v15, v15
	v_fmac_f32_e32 v132, v16, v16
	v_fmac_f32_e32 v134, v0, v0
	v_fmac_f32_e32 v132, v17, v17
	v_fmac_f32_e32 v134, v1, v1
	v_fmac_f32_e32 v132, v18, v18
	v_fmac_f32_e32 v134, v2, v2
	v_fmac_f32_e32 v132, v19, v19
	v_fmac_f32_e32 v134, v3, v3
	v_fmac_f32_e32 v132, v24, v24
	v_fmac_f32_e32 v134, v8, v8
	v_fmac_f32_e32 v132, v25, v25
	v_fmac_f32_e32 v134, v9, v9
	v_fmac_f32_e32 v132, v26, v26
	v_fmac_f32_e32 v134, v10, v10
	v_fmac_f32_e32 v132, v27, v27
	v_fmac_f32_e32 v134, v11, v11
	v_fmac_f32_e32 v132, v20, v20
	v_fmac_f32_e32 v134, v4, v4
	v_fmac_f32_e32 v132, v21, v21
	v_fmac_f32_e32 v134, v5, v5
	v_fmac_f32_e32 v132, v22, v22
	v_fmac_f32_e32 v134, v6, v6
	v_fmac_f32_e32 v132, v23, v23
	v_fmac_f32_e32 v134, v7, v7
	v_mbcnt_lo_u32_b32 v160, -1, 0
	v_mbcnt_hi_u32_b32 v160, -1, v160
	v_lshlrev_b32_e32 v160, 2, v160
	v_xor_b32_e32 v160, 0x80, v160
	ds_swizzle_b32 v149, v148 offset:swizzle(SWAP,16)
	ds_swizzle_b32 v151, v150 offset:swizzle(SWAP,16)
	ds_swizzle_b32 v153, v152 offset:swizzle(SWAP,16)
	ds_swizzle_b32 v155, v154 offset:swizzle(SWAP,16)
	ds_swizzle_b32 v157, v156 offset:swizzle(SWAP,16)
	ds_swizzle_b32 v159, v158 offset:swizzle(SWAP,16)
	ds_swizzle_b32 v133, v132 offset:swizzle(SWAP,16)
	ds_swizzle_b32 v135, v134 offset:swizzle(SWAP,16)
	s_waitcnt lgkmcnt(0)
	v_add_f32_e32 v148, v148, v149
	v_add_f32_e32 v150, v150, v151
	v_add_f32_e32 v152, v152, v153
	v_add_f32_e32 v154, v154, v155
	v_add_f32_e32 v156, v156, v157
	v_add_f32_e32 v158, v158, v159
	v_add_f32_e32 v132, v132, v133
	v_add_f32_e32 v134, v134, v135
	ds_bpermute_b32 v149, v160, v148
	ds_bpermute_b32 v151, v160, v150
	ds_bpermute_b32 v153, v160, v152
	ds_bpermute_b32 v155, v160, v154
	ds_bpermute_b32 v157, v160, v156
	ds_bpermute_b32 v159, v160, v158
	ds_bpermute_b32 v133, v160, v132
	ds_bpermute_b32 v135, v160, v134
	s_waitcnt lgkmcnt(0)
	v_add_f32_e32 v148, v148, v149
	v_add_f32_e32 v150, v150, v151
	v_add_f32_e32 v152, v152, v153
	v_add_f32_e32 v154, v154, v155
	v_add_f32_e32 v156, v156, v157
	v_add_f32_e32 v158, v158, v159
	v_add_f32_e32 v132, v132, v133
	v_add_f32_e32 v134, v134, v135
	v_fmamk_f32 v148, v148, 0x3c800000, v252
	v_fmamk_f32 v150, v150, 0x3c800000, v252
	v_fmamk_f32 v152, v152, 0x3c800000, v252
	v_fmamk_f32 v154, v154, 0x3c800000, v252
	v_fmamk_f32 v156, v156, 0x3c800000, v252
	v_fmamk_f32 v158, v158, 0x3c800000, v252
	v_fmamk_f32 v132, v132, 0x3c800000, v252
	v_fmamk_f32 v134, v134, 0x3c800000, v252
	v_rsq_f32_e32 v148, v148
	v_rsq_f32_e32 v150, v150
	v_rsq_f32_e32 v152, v152
	v_rsq_f32_e32 v154, v154
	v_rsq_f32_e32 v156, v156
	v_rsq_f32_e32 v158, v158
	v_rsq_f32_e32 v132, v132
	v_rsq_f32_e32 v134, v134
	v_mov_b32_e32 v149, v148
	v_mov_b32_e32 v151, v150
	v_mov_b32_e32 v153, v152
	v_mov_b32_e32 v155, v154
	v_mov_b32_e32 v157, v156
	v_mov_b32_e32 v159, v158
	v_mov_b32_e32 v133, v132
	v_mov_b32_e32 v135, v134
	s_and_b64 vcc, exec, s[24:25]
	s_cbranch_vccnz .Lqkv_g0
	s_waitcnt vmcnt(0)
.Lqkv_g0:
	s_waitcnt vmcnt(4)
	v_mov_b32_e32 v143, v131
	v_pk_mul_f32 v[116:117], v[116:117], v[148:149]
	v_pk_mul_f32 v[124:125], v[124:125], v[148:149]
	v_pk_mul_f32 v[118:119], v[118:119], v[148:149]
	v_pk_mul_f32 v[126:127], v[126:127], v[148:149]
	v_pk_mul_f32 v[116:117], v[198:199], v[116:117]
	v_pk_mul_f32 v[124:125], v[202:203], v[124:125]
	v_pk_mul_f32 v[118:119], v[200:201], v[118:119]
	v_pk_mul_f32 v[126:127], v[204:205], v[126:127]
	v_pk_mul_f32 v[136:137], v[124:125], v[218:219]
	v_pk_mul_f32 v[164:165], v[116:117], v[218:219]
	v_pk_mul_f32 v[138:139], v[126:127], v[220:221]
	v_pk_mul_f32 v[166:167], v[118:119], v[220:221]
	v_pk_fma_f32 v[116:117], v[116:117], v[214:215], v[136:137] neg_lo:[0,0,1] neg_hi:[0,0,1]
	v_pk_fma_f32 v[124:125], v[124:125], v[214:215], v[164:165]
	v_pk_fma_f32 v[118:119], v[118:119], v[216:217], v[138:139] neg_lo:[0,0,1] neg_hi:[0,0,1]
	v_pk_fma_f32 v[126:127], v[126:127], v[216:217], v[166:167]
	v_pk_mul_f32 v[116:117], v[116:117], s[16:17]
	v_pk_mul_f32 v[124:125], v[124:125], s[16:17]
	v_pk_mul_f32 v[118:119], v[118:119], s[16:17]
	v_pk_mul_f32 v[126:127], v[126:127], s[16:17]
	v_pk_mul_f32 v[112:113], v[112:113], v[148:149]
	v_pk_mul_f32 v[120:121], v[120:121], v[148:149]
	v_pk_mul_f32 v[114:115], v[114:115], v[148:149]
	v_pk_mul_f32 v[122:123], v[122:123], v[148:149]
	v_pk_mul_f32 v[112:113], v[206:207], v[112:113]
	v_pk_mul_f32 v[120:121], v[210:211], v[120:121]
	v_pk_mul_f32 v[114:115], v[208:209], v[114:115]
	v_pk_mul_f32 v[122:123], v[212:213], v[122:123]
	v_pk_mul_f32 v[136:137], v[120:121], v[226:227]
	v_pk_mul_f32 v[164:165], v[112:113], v[226:227]
	v_pk_mul_f32 v[138:139], v[122:123], v[228:229]
	v_pk_mul_f32 v[166:167], v[114:115], v[228:229]
	v_pk_fma_f32 v[112:113], v[112:113], v[222:223], v[136:137] neg_lo:[0,0,1] neg_hi:[0,0,1]
	v_pk_fma_f32 v[120:121], v[120:121], v[222:223], v[164:165]
	v_pk_fma_f32 v[114:115], v[114:115], v[224:225], v[138:139] neg_lo:[0,0,1] neg_hi:[0,0,1]
	v_pk_fma_f32 v[122:123], v[122:123], v[224:225], v[166:167]
	v_pk_mul_f32 v[112:113], v[112:113], s[16:17]
	v_pk_mul_f32 v[120:121], v[120:121], s[16:17]
	v_pk_mul_f32 v[114:115], v[114:115], s[16:17]
	v_pk_mul_f32 v[122:123], v[122:123], s[16:17]
	v_cvt_pk_bf16_f32 v172, v116, v117
	v_cvt_pk_bf16_f32 v173, v118, v119
	v_cvt_pk_bf16_f32 v174, v112, v113
	v_cvt_pk_bf16_f32 v175, v114, v115
	s_nop 1
	v_permlane32_swap_b32_e32 v172, v174
	v_permlane32_swap_b32_e32 v173, v175
	s_nop 1
	v_permlane16_swap_b32_e32 v172, v174
	v_permlane16_swap_b32_e32 v173, v175
	global_store_dwordx4 v143, v[172:175], s[66:67]
	s_nop 1
	v_cvt_pk_bf16_f32 v172, v124, v125
	v_cvt_pk_bf16_f32 v173, v126, v127
	v_cvt_pk_bf16_f32 v174, v120, v121
	v_cvt_pk_bf16_f32 v175, v122, v123
	s_nop 1
	v_permlane32_swap_b32_e32 v172, v174
	v_permlane32_swap_b32_e32 v173, v175
	s_nop 1
	v_permlane16_swap_b32_e32 v172, v174
	v_permlane16_swap_b32_e32 v173, v175
	global_store_dwordx4 v143, v[172:175], s[66:67] offset:64
	s_nop 1
	s_and_b64 vcc, exec, s[24:25]
	s_cbranch_vccz .Lqkv_nr0
	v_add_u32_e32 v168, 0x2000, v171
	global_load_dwordx4 v[214:217], v168, s[6:7]
	global_load_dwordx4 v[218:221], v168, s[6:7] offset:128
	global_load_dwordx4 v[222:225], v168, s[6:7] offset:64
	global_load_dwordx4 v[226:229], v168, s[6:7] offset:192
.Lqkv_nr0:
	s_waitcnt vmcnt(6)
	v_add_u32_e32 v143, 0xc000, v131
	v_pk_mul_f32 v[100:101], v[100:101], v[150:151]
	v_pk_mul_f32 v[108:109], v[108:109], v[150:151]
	v_pk_mul_f32 v[102:103], v[102:103], v[150:151]
	v_pk_mul_f32 v[110:111], v[110:111], v[150:151]
	v_pk_mul_f32 v[100:101], v[198:199], v[100:101]
	v_pk_mul_f32 v[108:109], v[202:203], v[108:109]
	v_pk_mul_f32 v[102:103], v[200:201], v[102:103]
	v_pk_mul_f32 v[110:111], v[204:205], v[110:111]
	v_pk_mul_f32 v[136:137], v[108:109], v[236:237]
	v_pk_mul_f32 v[164:165], v[100:101], v[236:237]
	v_pk_mul_f32 v[138:139], v[110:111], v[238:239]
	v_pk_mul_f32 v[166:167], v[102:103], v[238:239]
	v_pk_fma_f32 v[100:101], v[100:101], v[232:233], v[136:137] neg_lo:[0,0,1] neg_hi:[0,0,1]
	v_pk_fma_f32 v[108:109], v[108:109], v[232:233], v[164:165]
	v_pk_fma_f32 v[102:103], v[102:103], v[234:235], v[138:139] neg_lo:[0,0,1] neg_hi:[0,0,1]
	v_pk_fma_f32 v[110:111], v[110:111], v[234:235], v[166:167]
	v_pk_mul_f32 v[100:101], v[100:101], s[16:17]
	v_pk_mul_f32 v[108:109], v[108:109], s[16:17]
	v_pk_mul_f32 v[102:103], v[102:103], s[16:17]
	v_pk_mul_f32 v[110:111], v[110:111], s[16:17]
	v_pk_mul_f32 v[96:97], v[96:97], v[150:151]
	v_pk_mul_f32 v[104:105], v[104:105], v[150:151]
	v_pk_mul_f32 v[98:99], v[98:99], v[150:151]
	v_pk_mul_f32 v[106:107], v[106:107], v[150:151]
	v_pk_mul_f32 v[96:97], v[206:207], v[96:97]
	v_pk_mul_f32 v[104:105], v[210:211], v[104:105]
	v_pk_mul_f32 v[98:99], v[208:209], v[98:99]
	v_pk_mul_f32 v[106:107], v[212:213], v[106:107]
	v_pk_mul_f32 v[136:137], v[104:105], v[144:145]
	v_pk_mul_f32 v[164:165], v[96:97], v[144:145]
	v_pk_mul_f32 v[138:139], v[106:107], v[146:147]
	v_pk_mul_f32 v[166:167], v[98:99], v[146:147]
	v_pk_fma_f32 v[96:97], v[96:97], v[240:241], v[136:137] neg_lo:[0,0,1] neg_hi:[0,0,1]
	v_pk_fma_f32 v[104:105], v[104:105], v[240:241], v[164:165]
	v_pk_fma_f32 v[98:99], v[98:99], v[242:243], v[138:139] neg_lo:[0,0,1] neg_hi:[0,0,1]
	v_pk_fma_f32 v[106:107], v[106:107], v[242:243], v[166:167]
	v_pk_mul_f32 v[96:97], v[96:97], s[16:17]
	v_pk_mul_f32 v[104:105], v[104:105], s[16:17]
	v_pk_mul_f32 v[98:99], v[98:99], s[16:17]
	v_pk_mul_f32 v[106:107], v[106:107], s[16:17]
	v_cvt_pk_bf16_f32 v172, v100, v101
	v_cvt_pk_bf16_f32 v173, v102, v103
	v_cvt_pk_bf16_f32 v174, v96, v97
	v_cvt_pk_bf16_f32 v175, v98, v99
	s_nop 1
	v_permlane32_swap_b32_e32 v172, v174
	v_permlane32_swap_b32_e32 v173, v175
	s_nop 1
	v_permlane16_swap_b32_e32 v172, v174
	v_permlane16_swap_b32_e32 v173, v175
	global_store_dwordx4 v143, v[172:175], s[66:67]
	s_nop 1
	v_cvt_pk_bf16_f32 v172, v108, v109
	v_cvt_pk_bf16_f32 v173, v110, v111
	v_cvt_pk_bf16_f32 v174, v104, v105
	v_cvt_pk_bf16_f32 v175, v106, v107
	s_nop 1
	v_permlane32_swap_b32_e32 v172, v174
	v_permlane32_swap_b32_e32 v173, v175
	s_nop 1
	v_permlane16_swap_b32_e32 v172, v174
	v_permlane16_swap_b32_e32 v173, v175
	global_store_dwordx4 v143, v[172:175], s[66:67] offset:64
	s_nop 1
	s_and_b64 vcc, exec, s[24:25]
	s_cbranch_vccz .Lqkv_nr1
	v_add_u32_e32 v168, 0x3000, v171
	global_load_dwordx4 v[232:235], v168, s[6:7]
	global_load_dwordx4 v[236:239], v168, s[6:7] offset:128
	global_load_dwordx4 v[240:243], v168, s[6:7] offset:64
	global_load_dwordx4 v[144:147], v168, s[6:7] offset:192
.Lqkv_nr1:
	s_waitcnt vmcnt(6)
	v_add_u32_e32 v143, 0x18000, v131
	v_pk_mul_f32 v[84:85], v[84:85], v[152:153]
	v_pk_mul_f32 v[92:93], v[92:93], v[152:153]
	v_pk_mul_f32 v[86:87], v[86:87], v[152:153]
	v_pk_mul_f32 v[94:95], v[94:95], v[152:153]
	v_pk_mul_f32 v[84:85], v[198:199], v[84:85]
	v_pk_mul_f32 v[92:93], v[202:203], v[92:93]
	v_pk_mul_f32 v[86:87], v[200:201], v[86:87]
	v_pk_mul_f32 v[94:95], v[204:205], v[94:95]
	v_pk_mul_f32 v[136:137], v[92:93], v[218:219]
	v_pk_mul_f32 v[164:165], v[84:85], v[218:219]
	v_pk_mul_f32 v[138:139], v[94:95], v[220:221]
	v_pk_mul_f32 v[166:167], v[86:87], v[220:221]
	v_pk_fma_f32 v[84:85], v[84:85], v[214:215], v[136:137] neg_lo:[0,0,1] neg_hi:[0,0,1]
	v_pk_fma_f32 v[92:93], v[92:93], v[214:215], v[164:165]
	v_pk_fma_f32 v[86:87], v[86:87], v[216:217], v[138:139] neg_lo:[0,0,1] neg_hi:[0,0,1]
	v_pk_fma_f32 v[94:95], v[94:95], v[216:217], v[166:167]
	v_pk_mul_f32 v[84:85], v[84:85], s[16:17]
	v_pk_mul_f32 v[92:93], v[92:93], s[16:17]
	v_pk_mul_f32 v[86:87], v[86:87], s[16:17]
	v_pk_mul_f32 v[94:95], v[94:95], s[16:17]
	v_pk_mul_f32 v[80:81], v[80:81], v[152:153]
	v_pk_mul_f32 v[88:89], v[88:89], v[152:153]
	v_pk_mul_f32 v[82:83], v[82:83], v[152:153]
	v_pk_mul_f32 v[90:91], v[90:91], v[152:153]
	v_pk_mul_f32 v[80:81], v[206:207], v[80:81]
	v_pk_mul_f32 v[88:89], v[210:211], v[88:89]
	v_pk_mul_f32 v[82:83], v[208:209], v[82:83]
	v_pk_mul_f32 v[90:91], v[212:213], v[90:91]
	v_pk_mul_f32 v[136:137], v[88:89], v[226:227]
	v_pk_mul_f32 v[164:165], v[80:81], v[226:227]
	v_pk_mul_f32 v[138:139], v[90:91], v[228:229]
	v_pk_mul_f32 v[166:167], v[82:83], v[228:229]
	v_pk_fma_f32 v[80:81], v[80:81], v[222:223], v[136:137] neg_lo:[0,0,1] neg_hi:[0,0,1]
	v_pk_fma_f32 v[88:89], v[88:89], v[222:223], v[164:165]
	v_pk_fma_f32 v[82:83], v[82:83], v[224:225], v[138:139] neg_lo:[0,0,1] neg_hi:[0,0,1]
	v_pk_fma_f32 v[90:91], v[90:91], v[224:225], v[166:167]
	v_pk_mul_f32 v[80:81], v[80:81], s[16:17]
	v_pk_mul_f32 v[88:89], v[88:89], s[16:17]
	v_pk_mul_f32 v[82:83], v[82:83], s[16:17]
	v_pk_mul_f32 v[90:91], v[90:91], s[16:17]
	v_cvt_pk_bf16_f32 v172, v84, v85
	v_cvt_pk_bf16_f32 v173, v86, v87
	v_cvt_pk_bf16_f32 v174, v80, v81
	v_cvt_pk_bf16_f32 v175, v82, v83
	s_nop 1
	v_permlane32_swap_b32_e32 v172, v174
	v_permlane32_swap_b32_e32 v173, v175
	s_nop 1
	v_permlane16_swap_b32_e32 v172, v174
	v_permlane16_swap_b32_e32 v173, v175
	global_store_dwordx4 v143, v[172:175], s[66:67]
	s_nop 1
	v_cvt_pk_bf16_f32 v172, v92, v93
	v_cvt_pk_bf16_f32 v173, v94, v95
	v_cvt_pk_bf16_f32 v174, v88, v89
	v_cvt_pk_bf16_f32 v175, v90, v91
	s_nop 1
	v_permlane32_swap_b32_e32 v172, v174
	v_permlane32_swap_b32_e32 v173, v175
	s_nop 1
	v_permlane16_swap_b32_e32 v172, v174
	v_permlane16_swap_b32_e32 v173, v175
	global_store_dwordx4 v143, v[172:175], s[66:67] offset:64
	s_nop 1
	s_and_b64 vcc, exec, s[24:25]
	s_cbranch_vccz .Lqkv_nr2
	v_add_u32_e32 v168, 0x8000, v171
	global_load_dwordx4 v[214:217], v168, s[6:7]
	global_load_dwordx4 v[218:221], v168, s[6:7] offset:128
	global_load_dwordx4 v[222:225], v168, s[6:7] offset:64
	global_load_dwordx4 v[226:229], v168, s[6:7] offset:192
.Lqkv_nr2:
	s_waitcnt vmcnt(6)
	v_add_u32_e32 v143, 0x24000, v131
	v_pk_mul_f32 v[68:69], v[68:69], v[154:155]
	v_pk_mul_f32 v[76:77], v[76:77], v[154:155]
	v_pk_mul_f32 v[70:71], v[70:71], v[154:155]
	v_pk_mul_f32 v[78:79], v[78:79], v[154:155]
	v_pk_mul_f32 v[68:69], v[198:199], v[68:69]
	v_pk_mul_f32 v[76:77], v[202:203], v[76:77]
	v_pk_mul_f32 v[70:71], v[200:201], v[70:71]
	v_pk_mul_f32 v[78:79], v[204:205], v[78:79]
	v_pk_mul_f32 v[136:137], v[76:77], v[236:237]
	v_pk_mul_f32 v[164:165], v[68:69], v[236:237]
	v_pk_mul_f32 v[138:139], v[78:79], v[238:239]
	v_pk_mul_f32 v[166:167], v[70:71], v[238:239]
	v_pk_fma_f32 v[68:69], v[68:69], v[232:233], v[136:137] neg_lo:[0,0,1] neg_hi:[0,0,1]
	v_pk_fma_f32 v[76:77], v[76:77], v[232:233], v[164:165]
	v_pk_fma_f32 v[70:71], v[70:71], v[234:235], v[138:139] neg_lo:[0,0,1] neg_hi:[0,0,1]
	v_pk_fma_f32 v[78:79], v[78:79], v[234:235], v[166:167]
	v_pk_mul_f32 v[68:69], v[68:69], s[16:17]
	v_pk_mul_f32 v[76:77], v[76:77], s[16:17]
	v_pk_mul_f32 v[70:71], v[70:71], s[16:17]
	v_pk_mul_f32 v[78:79], v[78:79], s[16:17]
	v_pk_mul_f32 v[64:65], v[64:65], v[154:155]
	v_pk_mul_f32 v[72:73], v[72:73], v[154:155]
	v_pk_mul_f32 v[66:67], v[66:67], v[154:155]
	v_pk_mul_f32 v[74:75], v[74:75], v[154:155]
	v_pk_mul_f32 v[64:65], v[206:207], v[64:65]
	v_pk_mul_f32 v[72:73], v[210:211], v[72:73]
	v_pk_mul_f32 v[66:67], v[208:209], v[66:67]
	v_pk_mul_f32 v[74:75], v[212:213], v[74:75]
	v_pk_mul_f32 v[136:137], v[72:73], v[144:145]
	v_pk_mul_f32 v[164:165], v[64:65], v[144:145]
	v_pk_mul_f32 v[138:139], v[74:75], v[146:147]
	v_pk_mul_f32 v[166:167], v[66:67], v[146:147]
	v_pk_fma_f32 v[64:65], v[64:65], v[240:241], v[136:137] neg_lo:[0,0,1] neg_hi:[0,0,1]
	v_pk_fma_f32 v[72:73], v[72:73], v[240:241], v[164:165]
	v_pk_fma_f32 v[66:67], v[66:67], v[242:243], v[138:139] neg_lo:[0,0,1] neg_hi:[0,0,1]
	v_pk_fma_f32 v[74:75], v[74:75], v[242:243], v[166:167]
	v_pk_mul_f32 v[64:65], v[64:65], s[16:17]
	v_pk_mul_f32 v[72:73], v[72:73], s[16:17]
	v_pk_mul_f32 v[66:67], v[66:67], s[16:17]
	v_pk_mul_f32 v[74:75], v[74:75], s[16:17]
	v_cvt_pk_bf16_f32 v172, v68, v69
	v_cvt_pk_bf16_f32 v173, v70, v71
	v_cvt_pk_bf16_f32 v174, v64, v65
	v_cvt_pk_bf16_f32 v175, v66, v67
	s_nop 1
	v_permlane32_swap_b32_e32 v172, v174
	v_permlane32_swap_b32_e32 v173, v175
	s_nop 1
	v_permlane16_swap_b32_e32 v172, v174
	v_permlane16_swap_b32_e32 v173, v175
	global_store_dwordx4 v143, v[172:175], s[66:67]
	s_nop 1
	v_cvt_pk_bf16_f32 v172, v76, v77
	v_cvt_pk_bf16_f32 v173, v78, v79
	v_cvt_pk_bf16_f32 v174, v72, v73
	v_cvt_pk_bf16_f32 v175, v74, v75
	s_nop 1
	v_permlane32_swap_b32_e32 v172, v174
	v_permlane32_swap_b32_e32 v173, v175
	s_nop 1
	v_permlane16_swap_b32_e32 v172, v174
	v_permlane16_swap_b32_e32 v173, v175
	global_store_dwordx4 v143, v[172:175], s[66:67] offset:64
	s_nop 1
	s_and_b64 vcc, exec, s[24:25]
	s_cbranch_vccz .Lqkv_nr3
	v_add_u32_e32 v168, 0x9000, v171
	global_load_dwordx4 v[232:235], v168, s[6:7]
	global_load_dwordx4 v[236:239], v168, s[6:7] offset:128
	global_load_dwordx4 v[240:243], v168, s[6:7] offset:64
	global_load_dwordx4 v[144:147], v168, s[6:7] offset:192
.Lqkv_nr3:
	s_waitcnt vmcnt(6)
	v_add_u32_e32 v143, 0x60000, v131
	v_pk_mul_f32 v[60:61], v[60:61], v[156:157]
	v_pk_mul_f32 v[56:57], v[56:57], v[156:157]
	v_pk_mul_f32 v[62:63], v[62:63], v[156:157]
	v_pk_mul_f32 v[58:59], v[58:59], v[156:157]
	v_pk_mul_f32 v[60:61], v[198:199], v[60:61]
	v_pk_mul_f32 v[56:57], v[202:203], v[56:57]
	v_pk_mul_f32 v[62:63], v[200:201], v[62:63]
	v_pk_mul_f32 v[58:59], v[204:205], v[58:59]
	v_pk_mul_f32 v[136:137], v[56:57], v[218:219]
	v_pk_mul_f32 v[164:165], v[60:61], v[218:219]
	v_pk_mul_f32 v[138:139], v[58:59], v[220:221]
	v_pk_mul_f32 v[166:167], v[62:63], v[220:221]
	v_pk_fma_f32 v[60:61], v[60:61], v[214:215], v[136:137] neg_lo:[0,0,1] neg_hi:[0,0,1]
	v_pk_fma_f32 v[56:57], v[56:57], v[214:215], v[164:165]
	v_pk_fma_f32 v[62:63], v[62:63], v[216:217], v[138:139] neg_lo:[0,0,1] neg_hi:[0,0,1]
	v_pk_fma_f32 v[58:59], v[58:59], v[216:217], v[166:167]
	v_pk_mul_f32 v[60:61], v[60:61], s[16:17]
	v_pk_mul_f32 v[56:57], v[56:57], s[16:17]
	v_pk_mul_f32 v[62:63], v[62:63], s[16:17]
	v_pk_mul_f32 v[58:59], v[58:59], s[16:17]
	v_pk_mul_f32 v[48:49], v[48:49], v[156:157]
	v_pk_mul_f32 v[52:53], v[52:53], v[156:157]
	v_pk_mul_f32 v[50:51], v[50:51], v[156:157]
	v_pk_mul_f32 v[54:55], v[54:55], v[156:157]
	v_pk_mul_f32 v[48:49], v[206:207], v[48:49]
	v_pk_mul_f32 v[52:53], v[210:211], v[52:53]
	v_pk_mul_f32 v[50:51], v[208:209], v[50:51]
	v_pk_mul_f32 v[54:55], v[212:213], v[54:55]
	v_pk_mul_f32 v[136:137], v[52:53], v[226:227]
	v_pk_mul_f32 v[164:165], v[48:49], v[226:227]
	v_pk_mul_f32 v[138:139], v[54:55], v[228:229]
	v_pk_mul_f32 v[166:167], v[50:51], v[228:229]
	v_pk_fma_f32 v[48:49], v[48:49], v[222:223], v[136:137] neg_lo:[0,0,1] neg_hi:[0,0,1]
	v_pk_fma_f32 v[52:53], v[52:53], v[222:223], v[164:165]
	v_pk_fma_f32 v[50:51], v[50:51], v[224:225], v[138:139] neg_lo:[0,0,1] neg_hi:[0,0,1]
	v_pk_fma_f32 v[54:55], v[54:55], v[224:225], v[166:167]
	v_pk_mul_f32 v[48:49], v[48:49], s[16:17]
	v_pk_mul_f32 v[52:53], v[52:53], s[16:17]
	v_pk_mul_f32 v[50:51], v[50:51], s[16:17]
	v_pk_mul_f32 v[54:55], v[54:55], s[16:17]
	v_cvt_pk_bf16_f32 v172, v60, v61
	v_cvt_pk_bf16_f32 v173, v62, v63
	v_cvt_pk_bf16_f32 v174, v48, v49
	v_cvt_pk_bf16_f32 v175, v50, v51
	s_nop 1
	v_permlane32_swap_b32_e32 v172, v174
	v_permlane32_swap_b32_e32 v173, v175
	s_nop 1
	v_permlane16_swap_b32_e32 v172, v174
	v_permlane16_swap_b32_e32 v173, v175
	global_store_dwordx4 v143, v[172:175], s[66:67]
	s_nop 1
	v_cvt_pk_bf16_f32 v172, v56, v57
	v_cvt_pk_bf16_f32 v173, v58, v59
	v_cvt_pk_bf16_f32 v174, v52, v53
	v_cvt_pk_bf16_f32 v175, v54, v55
	s_nop 1
	v_permlane32_swap_b32_e32 v172, v174
	v_permlane32_swap_b32_e32 v173, v175
	s_nop 1
	v_permlane16_swap_b32_e32 v172, v174
	v_permlane16_swap_b32_e32 v173, v175
	global_store_dwordx4 v143, v[172:175], s[66:67] offset:64
	s_nop 1
	s_and_b64 vcc, exec, s[24:25]
	s_cbranch_vccz .Lqkv_nr4
	v_add_u32_e32 v168, 0xa000, v171
	global_load_dwordx4 v[214:217], v168, s[6:7]
	global_load_dwordx4 v[218:221], v168, s[6:7] offset:128
	global_load_dwordx4 v[222:225], v168, s[6:7] offset:64
	global_load_dwordx4 v[226:229], v168, s[6:7] offset:192
.Lqkv_nr4:
	s_waitcnt vmcnt(6)
	v_add_u32_e32 v143, 0x6c000, v131
	v_pk_mul_f32 v[44:45], v[44:45], v[158:159]
	v_pk_mul_f32 v[40:41], v[40:41], v[158:159]
	v_pk_mul_f32 v[46:47], v[46:47], v[158:159]
	v_pk_mul_f32 v[42:43], v[42:43], v[158:159]
	v_pk_mul_f32 v[44:45], v[198:199], v[44:45]
	v_pk_mul_f32 v[40:41], v[202:203], v[40:41]
	v_pk_mul_f32 v[46:47], v[200:201], v[46:47]
	v_pk_mul_f32 v[42:43], v[204:205], v[42:43]
	v_pk_mul_f32 v[136:137], v[40:41], v[236:237]
	v_pk_mul_f32 v[164:165], v[44:45], v[236:237]
	v_pk_mul_f32 v[138:139], v[42:43], v[238:239]
	v_pk_mul_f32 v[166:167], v[46:47], v[238:239]
	v_pk_fma_f32 v[44:45], v[44:45], v[232:233], v[136:137] neg_lo:[0,0,1] neg_hi:[0,0,1]
	v_pk_fma_f32 v[40:41], v[40:41], v[232:233], v[164:165]
	v_pk_fma_f32 v[46:47], v[46:47], v[234:235], v[138:139] neg_lo:[0,0,1] neg_hi:[0,0,1]
	v_pk_fma_f32 v[42:43], v[42:43], v[234:235], v[166:167]
	v_pk_mul_f32 v[44:45], v[44:45], s[16:17]
	v_pk_mul_f32 v[40:41], v[40:41], s[16:17]
	v_pk_mul_f32 v[46:47], v[46:47], s[16:17]
	v_pk_mul_f32 v[42:43], v[42:43], s[16:17]
	v_pk_mul_f32 v[32:33], v[32:33], v[158:159]
	v_pk_mul_f32 v[36:37], v[36:37], v[158:159]
	v_pk_mul_f32 v[34:35], v[34:35], v[158:159]
	v_pk_mul_f32 v[38:39], v[38:39], v[158:159]
	v_pk_mul_f32 v[32:33], v[206:207], v[32:33]
	v_pk_mul_f32 v[36:37], v[210:211], v[36:37]
	v_pk_mul_f32 v[34:35], v[208:209], v[34:35]
	v_pk_mul_f32 v[38:39], v[212:213], v[38:39]
	v_pk_mul_f32 v[136:137], v[36:37], v[144:145]
	v_pk_mul_f32 v[164:165], v[32:33], v[144:145]
	v_pk_mul_f32 v[138:139], v[38:39], v[146:147]
	v_pk_mul_f32 v[166:167], v[34:35], v[146:147]
	v_pk_fma_f32 v[32:33], v[32:33], v[240:241], v[136:137] neg_lo:[0,0,1] neg_hi:[0,0,1]
	v_pk_fma_f32 v[36:37], v[36:37], v[240:241], v[164:165]
	v_pk_fma_f32 v[34:35], v[34:35], v[242:243], v[138:139] neg_lo:[0,0,1] neg_hi:[0,0,1]
	v_pk_fma_f32 v[38:39], v[38:39], v[242:243], v[166:167]
	v_pk_mul_f32 v[32:33], v[32:33], s[16:17]
	v_pk_mul_f32 v[36:37], v[36:37], s[16:17]
	v_pk_mul_f32 v[34:35], v[34:35], s[16:17]
	v_pk_mul_f32 v[38:39], v[38:39], s[16:17]
	v_cvt_pk_bf16_f32 v172, v44, v45
	v_cvt_pk_bf16_f32 v173, v46, v47
	v_cvt_pk_bf16_f32 v174, v32, v33
	v_cvt_pk_bf16_f32 v175, v34, v35
	s_nop 1
	v_permlane32_swap_b32_e32 v172, v174
	v_permlane32_swap_b32_e32 v173, v175
	s_nop 1
	v_permlane16_swap_b32_e32 v172, v174
	v_permlane16_swap_b32_e32 v173, v175
	global_store_dwordx4 v143, v[172:175], s[66:67]
	s_nop 1
	v_cvt_pk_bf16_f32 v172, v40, v41
	v_cvt_pk_bf16_f32 v173, v42, v43
	v_cvt_pk_bf16_f32 v174, v36, v37
	v_cvt_pk_bf16_f32 v175, v38, v39
	s_nop 1
	v_permlane32_swap_b32_e32 v172, v174
	v_permlane32_swap_b32_e32 v173, v175
	s_nop 1
	v_permlane16_swap_b32_e32 v172, v174
	v_permlane16_swap_b32_e32 v173, v175
	global_store_dwordx4 v143, v[172:175], s[66:67] offset:64
	s_nop 1
	s_and_b64 vcc, exec, s[24:25]
	s_cbranch_vccz .Lqkv_nr5
	v_add_u32_e32 v168, 0xb000, v171
	global_load_dwordx4 v[232:235], v168, s[6:7]
	global_load_dwordx4 v[236:239], v168, s[6:7] offset:128
	global_load_dwordx4 v[240:243], v168, s[6:7] offset:64
	global_load_dwordx4 v[144:147], v168, s[6:7] offset:192
.Lqkv_nr5:
	s_waitcnt vmcnt(6)
	v_add_u32_e32 v143, 0x78000, v131
	v_pk_mul_f32 v[28:29], v[28:29], v[132:133]
	v_pk_mul_f32 v[24:25], v[24:25], v[132:133]
	v_pk_mul_f32 v[30:31], v[30:31], v[132:133]
	v_pk_mul_f32 v[26:27], v[26:27], v[132:133]
	v_pk_mul_f32 v[28:29], v[198:199], v[28:29]
	v_pk_mul_f32 v[24:25], v[202:203], v[24:25]
	v_pk_mul_f32 v[30:31], v[200:201], v[30:31]
	v_pk_mul_f32 v[26:27], v[204:205], v[26:27]
	v_pk_mul_f32 v[136:137], v[24:25], v[218:219]
	v_pk_mul_f32 v[164:165], v[28:29], v[218:219]
	v_pk_mul_f32 v[138:139], v[26:27], v[220:221]
	v_pk_mul_f32 v[166:167], v[30:31], v[220:221]
	v_pk_fma_f32 v[28:29], v[28:29], v[214:215], v[136:137] neg_lo:[0,0,1] neg_hi:[0,0,1]
	v_pk_fma_f32 v[24:25], v[24:25], v[214:215], v[164:165]
	v_pk_fma_f32 v[30:31], v[30:31], v[216:217], v[138:139] neg_lo:[0,0,1] neg_hi:[0,0,1]
	v_pk_fma_f32 v[26:27], v[26:27], v[216:217], v[166:167]
	v_pk_mul_f32 v[28:29], v[28:29], s[16:17]
	v_pk_mul_f32 v[24:25], v[24:25], s[16:17]
	v_pk_mul_f32 v[30:31], v[30:31], s[16:17]
	v_pk_mul_f32 v[26:27], v[26:27], s[16:17]
	v_pk_mul_f32 v[16:17], v[16:17], v[132:133]
	v_pk_mul_f32 v[20:21], v[20:21], v[132:133]
	v_pk_mul_f32 v[18:19], v[18:19], v[132:133]
	v_pk_mul_f32 v[22:23], v[22:23], v[132:133]
	v_pk_mul_f32 v[16:17], v[206:207], v[16:17]
	v_pk_mul_f32 v[20:21], v[210:211], v[20:21]
	v_pk_mul_f32 v[18:19], v[208:209], v[18:19]
	v_pk_mul_f32 v[22:23], v[212:213], v[22:23]
	v_pk_mul_f32 v[136:137], v[20:21], v[226:227]
	v_pk_mul_f32 v[164:165], v[16:17], v[226:227]
	v_pk_mul_f32 v[138:139], v[22:23], v[228:229]
	v_pk_mul_f32 v[166:167], v[18:19], v[228:229]
	v_pk_fma_f32 v[16:17], v[16:17], v[222:223], v[136:137] neg_lo:[0,0,1] neg_hi:[0,0,1]
	v_pk_fma_f32 v[20:21], v[20:21], v[222:223], v[164:165]
	v_pk_fma_f32 v[18:19], v[18:19], v[224:225], v[138:139] neg_lo:[0,0,1] neg_hi:[0,0,1]
	v_pk_fma_f32 v[22:23], v[22:23], v[224:225], v[166:167]
	v_pk_mul_f32 v[16:17], v[16:17], s[16:17]
	v_pk_mul_f32 v[20:21], v[20:21], s[16:17]
	v_pk_mul_f32 v[18:19], v[18:19], s[16:17]
	v_pk_mul_f32 v[22:23], v[22:23], s[16:17]
	v_cvt_pk_bf16_f32 v172, v28, v29
	v_cvt_pk_bf16_f32 v173, v30, v31
	v_cvt_pk_bf16_f32 v174, v16, v17
	v_cvt_pk_bf16_f32 v175, v18, v19
	s_nop 1
	v_permlane32_swap_b32_e32 v172, v174
	v_permlane32_swap_b32_e32 v173, v175
	s_nop 1
	v_permlane16_swap_b32_e32 v172, v174
	v_permlane16_swap_b32_e32 v173, v175
	global_store_dwordx4 v143, v[172:175], s[66:67]
	s_nop 1
	v_cvt_pk_bf16_f32 v172, v24, v25
	v_cvt_pk_bf16_f32 v173, v26, v27
	v_cvt_pk_bf16_f32 v174, v20, v21
	v_cvt_pk_bf16_f32 v175, v22, v23
	s_nop 1
	v_permlane32_swap_b32_e32 v172, v174
	v_permlane32_swap_b32_e32 v173, v175
	s_nop 1
	v_permlane16_swap_b32_e32 v172, v174
	v_permlane16_swap_b32_e32 v173, v175
	global_store_dwordx4 v143, v[172:175], s[66:67] offset:64
	s_nop 1
	s_waitcnt vmcnt(2)
	v_add_u32_e32 v143, 0x84000, v131
	v_pk_mul_f32 v[12:13], v[12:13], v[134:135]
	v_pk_mul_f32 v[8:9], v[8:9], v[134:135]
	v_pk_mul_f32 v[14:15], v[14:15], v[134:135]
	v_pk_mul_f32 v[10:11], v[10:11], v[134:135]
	v_pk_mul_f32 v[12:13], v[198:199], v[12:13]
	v_pk_mul_f32 v[8:9], v[202:203], v[8:9]
	v_pk_mul_f32 v[14:15], v[200:201], v[14:15]
	v_pk_mul_f32 v[10:11], v[204:205], v[10:11]
	v_pk_mul_f32 v[136:137], v[8:9], v[236:237]
	v_pk_mul_f32 v[164:165], v[12:13], v[236:237]
	v_pk_mul_f32 v[138:139], v[10:11], v[238:239]
	v_pk_mul_f32 v[166:167], v[14:15], v[238:239]
	v_pk_fma_f32 v[12:13], v[12:13], v[232:233], v[136:137] neg_lo:[0,0,1] neg_hi:[0,0,1]
	v_pk_fma_f32 v[8:9], v[8:9], v[232:233], v[164:165]
	v_pk_fma_f32 v[14:15], v[14:15], v[234:235], v[138:139] neg_lo:[0,0,1] neg_hi:[0,0,1]
	v_pk_fma_f32 v[10:11], v[10:11], v[234:235], v[166:167]
	v_pk_mul_f32 v[12:13], v[12:13], s[16:17]
	v_pk_mul_f32 v[8:9], v[8:9], s[16:17]
	v_pk_mul_f32 v[14:15], v[14:15], s[16:17]
	v_pk_mul_f32 v[10:11], v[10:11], s[16:17]
	v_pk_mul_f32 v[0:1], v[0:1], v[134:135]
	v_pk_mul_f32 v[4:5], v[4:5], v[134:135]
	v_pk_mul_f32 v[2:3], v[2:3], v[134:135]
	v_pk_mul_f32 v[6:7], v[6:7], v[134:135]
	v_pk_mul_f32 v[0:1], v[206:207], v[0:1]
	v_pk_mul_f32 v[4:5], v[210:211], v[4:5]
	v_pk_mul_f32 v[2:3], v[208:209], v[2:3]
	v_pk_mul_f32 v[6:7], v[212:213], v[6:7]
	v_pk_mul_f32 v[136:137], v[4:5], v[144:145]
	v_pk_mul_f32 v[164:165], v[0:1], v[144:145]
	v_pk_mul_f32 v[138:139], v[6:7], v[146:147]
	v_pk_mul_f32 v[166:167], v[2:3], v[146:147]
	v_pk_fma_f32 v[0:1], v[0:1], v[240:241], v[136:137] neg_lo:[0,0,1] neg_hi:[0,0,1]
	v_pk_fma_f32 v[4:5], v[4:5], v[240:241], v[164:165]
	v_pk_fma_f32 v[2:3], v[2:3], v[242:243], v[138:139] neg_lo:[0,0,1] neg_hi:[0,0,1]
	v_pk_fma_f32 v[6:7], v[6:7], v[242:243], v[166:167]
	v_pk_mul_f32 v[0:1], v[0:1], s[16:17]
	v_pk_mul_f32 v[4:5], v[4:5], s[16:17]
	v_pk_mul_f32 v[2:3], v[2:3], s[16:17]
	v_pk_mul_f32 v[6:7], v[6:7], s[16:17]
	v_cvt_pk_bf16_f32 v172, v12, v13
	v_cvt_pk_bf16_f32 v173, v14, v15
	v_cvt_pk_bf16_f32 v174, v0, v1
	v_cvt_pk_bf16_f32 v175, v2, v3
	s_nop 1
	v_permlane32_swap_b32_e32 v172, v174
	v_permlane32_swap_b32_e32 v173, v175
	s_nop 1
	v_permlane16_swap_b32_e32 v172, v174
	v_permlane16_swap_b32_e32 v173, v175
	global_store_dwordx4 v143, v[172:175], s[66:67]
	s_nop 1
	v_cvt_pk_bf16_f32 v172, v8, v9
	v_cvt_pk_bf16_f32 v173, v10, v11
	v_cvt_pk_bf16_f32 v174, v4, v5
	v_cvt_pk_bf16_f32 v175, v6, v7
	s_nop 1
	v_permlane32_swap_b32_e32 v172, v174
	v_permlane32_swap_b32_e32 v173, v175
	s_nop 1
	v_permlane16_swap_b32_e32 v172, v174
	v_permlane16_swap_b32_e32 v173, v175
	global_store_dwordx4 v143, v[172:175], s[66:67] offset:64
	s_nop 1
	s_branch .Lqkv_end
.Lqkv_v:
	v_mov_b32_e32 v143, v131
	v_cvt_pk_bf16_f32 v172, v116, v117
	v_cvt_pk_bf16_f32 v173, v118, v119
	v_cvt_pk_bf16_f32 v174, v112, v113
	v_cvt_pk_bf16_f32 v175, v114, v115
	s_nop 1
	v_permlane32_swap_b32_e32 v172, v174
	v_permlane32_swap_b32_e32 v173, v175
	s_nop 1
	v_permlane16_swap_b32_e32 v172, v174
	v_permlane16_swap_b32_e32 v173, v175
	global_store_dwordx4 v143, v[172:175], s[66:67]
	s_nop 1
	v_cvt_pk_bf16_f32 v172, v124, v125
	v_cvt_pk_bf16_f32 v173, v126, v127
	v_cvt_pk_bf16_f32 v174, v120, v121
	v_cvt_pk_bf16_f32 v175, v122, v123
	s_nop 1
	v_permlane32_swap_b32_e32 v172, v174
	v_permlane32_swap_b32_e32 v173, v175
	s_nop 1
	v_permlane16_swap_b32_e32 v172, v174
	v_permlane16_swap_b32_e32 v173, v175
	global_store_dwordx4 v143, v[172:175], s[66:67] offset:64
	s_nop 1
	v_add_u32_e32 v143, 0xc000, v131
	v_cvt_pk_bf16_f32 v172, v100, v101
	v_cvt_pk_bf16_f32 v173, v102, v103
	v_cvt_pk_bf16_f32 v174, v96, v97
	v_cvt_pk_bf16_f32 v175, v98, v99
	s_nop 1
	v_permlane32_swap_b32_e32 v172, v174
	v_permlane32_swap_b32_e32 v173, v175
	s_nop 1
	v_permlane16_swap_b32_e32 v172, v174
	v_permlane16_swap_b32_e32 v173, v175
	global_store_dwordx4 v143, v[172:175], s[66:67]
	s_nop 1
	v_cvt_pk_bf16_f32 v172, v108, v109
	v_cvt_pk_bf16_f32 v173, v110, v111
	v_cvt_pk_bf16_f32 v174, v104, v105
	v_cvt_pk_bf16_f32 v175, v106, v107
	s_nop 1
	v_permlane32_swap_b32_e32 v172, v174
	v_permlane32_swap_b32_e32 v173, v175
	s_nop 1
	v_permlane16_swap_b32_e32 v172, v174
	v_permlane16_swap_b32_e32 v173, v175
	global_store_dwordx4 v143, v[172:175], s[66:67] offset:64
	s_nop 1
	v_add_u32_e32 v143, 0x18000, v131
	v_cvt_pk_bf16_f32 v172, v84, v85
	v_cvt_pk_bf16_f32 v173, v86, v87
	v_cvt_pk_bf16_f32 v174, v80, v81
	v_cvt_pk_bf16_f32 v175, v82, v83
	s_nop 1
	v_permlane32_swap_b32_e32 v172, v174
	v_permlane32_swap_b32_e32 v173, v175
	s_nop 1
	v_permlane16_swap_b32_e32 v172, v174
	v_permlane16_swap_b32_e32 v173, v175
	global_store_dwordx4 v143, v[172:175], s[66:67]
	s_nop 1
	v_cvt_pk_bf16_f32 v172, v92, v93
	v_cvt_pk_bf16_f32 v173, v94, v95
	v_cvt_pk_bf16_f32 v174, v88, v89
	v_cvt_pk_bf16_f32 v175, v90, v91
	s_nop 1
	v_permlane32_swap_b32_e32 v172, v174
	v_permlane32_swap_b32_e32 v173, v175
	s_nop 1
	v_permlane16_swap_b32_e32 v172, v174
	v_permlane16_swap_b32_e32 v173, v175
	global_store_dwordx4 v143, v[172:175], s[66:67] offset:64
	s_nop 1
	v_add_u32_e32 v143, 0x24000, v131
	v_cvt_pk_bf16_f32 v172, v68, v69
	v_cvt_pk_bf16_f32 v173, v70, v71
	v_cvt_pk_bf16_f32 v174, v64, v65
	v_cvt_pk_bf16_f32 v175, v66, v67
	s_nop 1
	v_permlane32_swap_b32_e32 v172, v174
	v_permlane32_swap_b32_e32 v173, v175
	s_nop 1
	v_permlane16_swap_b32_e32 v172, v174
	v_permlane16_swap_b32_e32 v173, v175
	global_store_dwordx4 v143, v[172:175], s[66:67]
	s_nop 1
	v_cvt_pk_bf16_f32 v172, v76, v77
	v_cvt_pk_bf16_f32 v173, v78, v79
	v_cvt_pk_bf16_f32 v174, v72, v73
	v_cvt_pk_bf16_f32 v175, v74, v75
	s_nop 1
	v_permlane32_swap_b32_e32 v172, v174
	v_permlane32_swap_b32_e32 v173, v175
	s_nop 1
	v_permlane16_swap_b32_e32 v172, v174
	v_permlane16_swap_b32_e32 v173, v175
	global_store_dwordx4 v143, v[172:175], s[66:67] offset:64
	s_nop 1
	v_add_u32_e32 v143, 0x60000, v131
	v_cvt_pk_bf16_f32 v172, v60, v61
	v_cvt_pk_bf16_f32 v173, v62, v63
	v_cvt_pk_bf16_f32 v174, v48, v49
	v_cvt_pk_bf16_f32 v175, v50, v51
	s_nop 1
	v_permlane32_swap_b32_e32 v172, v174
	v_permlane32_swap_b32_e32 v173, v175
	s_nop 1
	v_permlane16_swap_b32_e32 v172, v174
	v_permlane16_swap_b32_e32 v173, v175
	global_store_dwordx4 v143, v[172:175], s[66:67]
	s_nop 1
	v_cvt_pk_bf16_f32 v172, v56, v57
	v_cvt_pk_bf16_f32 v173, v58, v59
	v_cvt_pk_bf16_f32 v174, v52, v53
	v_cvt_pk_bf16_f32 v175, v54, v55
	s_nop 1
	v_permlane32_swap_b32_e32 v172, v174
	v_permlane32_swap_b32_e32 v173, v175
	s_nop 1
	v_permlane16_swap_b32_e32 v172, v174
	v_permlane16_swap_b32_e32 v173, v175
	global_store_dwordx4 v143, v[172:175], s[66:67] offset:64
	s_nop 1
	v_add_u32_e32 v143, 0x6c000, v131
	v_cvt_pk_bf16_f32 v172, v44, v45
	v_cvt_pk_bf16_f32 v173, v46, v47
	v_cvt_pk_bf16_f32 v174, v32, v33
	v_cvt_pk_bf16_f32 v175, v34, v35
	s_nop 1
	v_permlane32_swap_b32_e32 v172, v174
	v_permlane32_swap_b32_e32 v173, v175
	s_nop 1
	v_permlane16_swap_b32_e32 v172, v174
	v_permlane16_swap_b32_e32 v173, v175
	global_store_dwordx4 v143, v[172:175], s[66:67]
	s_nop 1
	v_cvt_pk_bf16_f32 v172, v40, v41
	v_cvt_pk_bf16_f32 v173, v42, v43
	v_cvt_pk_bf16_f32 v174, v36, v37
	v_cvt_pk_bf16_f32 v175, v38, v39
	s_nop 1
	v_permlane32_swap_b32_e32 v172, v174
	v_permlane32_swap_b32_e32 v173, v175
	s_nop 1
	v_permlane16_swap_b32_e32 v172, v174
	v_permlane16_swap_b32_e32 v173, v175
	global_store_dwordx4 v143, v[172:175], s[66:67] offset:64
	s_nop 1
	v_add_u32_e32 v143, 0x78000, v131
	v_cvt_pk_bf16_f32 v172, v28, v29
	v_cvt_pk_bf16_f32 v173, v30, v31
	v_cvt_pk_bf16_f32 v174, v16, v17
	v_cvt_pk_bf16_f32 v175, v18, v19
	s_nop 1
	v_permlane32_swap_b32_e32 v172, v174
	v_permlane32_swap_b32_e32 v173, v175
	s_nop 1
	v_permlane16_swap_b32_e32 v172, v174
	v_permlane16_swap_b32_e32 v173, v175
	global_store_dwordx4 v143, v[172:175], s[66:67]
	s_nop 1
	v_cvt_pk_bf16_f32 v172, v24, v25
	v_cvt_pk_bf16_f32 v173, v26, v27
	v_cvt_pk_bf16_f32 v174, v20, v21
	v_cvt_pk_bf16_f32 v175, v22, v23
	s_nop 1
	v_permlane32_swap_b32_e32 v172, v174
	v_permlane32_swap_b32_e32 v173, v175
	s_nop 1
	v_permlane16_swap_b32_e32 v172, v174
	v_permlane16_swap_b32_e32 v173, v175
	global_store_dwordx4 v143, v[172:175], s[66:67] offset:64
	s_nop 1
	v_add_u32_e32 v143, 0x84000, v131
	v_cvt_pk_bf16_f32 v172, v12, v13
	v_cvt_pk_bf16_f32 v173, v14, v15
	v_cvt_pk_bf16_f32 v174, v0, v1
	v_cvt_pk_bf16_f32 v175, v2, v3
	s_nop 1
	v_permlane32_swap_b32_e32 v172, v174
	v_permlane32_swap_b32_e32 v173, v175
	s_nop 1
	v_permlane16_swap_b32_e32 v172, v174
	v_permlane16_swap_b32_e32 v173, v175
	global_store_dwordx4 v143, v[172:175], s[66:67]
	s_nop 1
	v_cvt_pk_bf16_f32 v172, v8, v9
	v_cvt_pk_bf16_f32 v173, v10, v11
	v_cvt_pk_bf16_f32 v174, v4, v5
	v_cvt_pk_bf16_f32 v175, v6, v7
	s_nop 1
	v_permlane32_swap_b32_e32 v172, v174
	v_permlane32_swap_b32_e32 v173, v175
	s_nop 1
	v_permlane16_swap_b32_e32 v172, v174
	v_permlane16_swap_b32_e32 v173, v175
	global_store_dwordx4 v143, v[172:175], s[66:67] offset:64
	s_nop 1
.Lqkv_end:
	s_waitcnt vmcnt(0)
	s_add_i32 s21, s21, s20
	s_cmpk_gt_i32 s21, 0x18b
	s_cbranch_scc1 .LBB0_166
	s_branch .LBB0_109

.LBB0_324:
	s_or_b64 exec, exec, s[6:7]
	v_add_u32_e32 v128, s4, v143
	v_lshlrev_b32_e32 v129, 6, v142
	v_lshl_or_b32 v129, v141, 4, v129
	s_lshl_b32 s0, s14, 8
	v_add_u32_e32 v129, s0, v129
	s_movk_i32 s1, 0x1600
	v_mad_u32_u24 v130, v128, s1, v129
	s_mov_b32 s2, 0xbfb8aa3b
	s_mov_b32 s3, 0xbfb8aa3b
	s_mov_b32 s28, 1.0
	s_mov_b32 s29, 1.0
	v_mov_b32_e32 v131, v130
	v_pk_mul_f32 v[132:133], v[120:121], s[2:3]
	v_pk_mul_f32 v[134:135], v[122:123], s[2:3]
	v_exp_f32_e32 v132, v132
	v_exp_f32_e32 v133, v133
	v_exp_f32_e32 v134, v134
	v_exp_f32_e32 v135, v135
	v_pk_mul_f32 v[136:137], v[112:113], s[2:3]
	v_pk_mul_f32 v[138:139], v[114:115], s[2:3]
	v_exp_f32_e32 v136, v136
	v_exp_f32_e32 v137, v137
	v_exp_f32_e32 v138, v138
	v_exp_f32_e32 v139, v139
	v_pk_add_f32 v[132:133], v[132:133], s[28:29]
	v_pk_add_f32 v[134:135], v[134:135], s[28:29]
	v_rcp_f32_e32 v132, v132
	v_rcp_f32_e32 v133, v133
	v_rcp_f32_e32 v134, v134
	v_rcp_f32_e32 v135, v135
	v_pk_add_f32 v[136:137], v[136:137], s[28:29]
	v_pk_add_f32 v[138:139], v[138:139], s[28:29]
	v_rcp_f32_e32 v136, v136
	v_rcp_f32_e32 v137, v137
	v_rcp_f32_e32 v138, v138
	v_rcp_f32_e32 v139, v139
	v_pk_mul_f32 v[120:121], v[120:121], v[132:133]
	v_pk_mul_f32 v[122:123], v[122:123], v[134:135]
	v_pk_mul_f32 v[120:121], v[120:121], v[124:125]
	v_pk_mul_f32 v[122:123], v[122:123], v[126:127]
	v_cvt_pk_bf16_f32 v144, v120, v121
	v_cvt_pk_bf16_f32 v145, v122, v123
	v_pk_mul_f32 v[112:113], v[112:113], v[136:137]
	v_pk_mul_f32 v[114:115], v[114:115], v[138:139]
	v_pk_mul_f32 v[112:113], v[112:113], v[116:117]
	v_pk_mul_f32 v[114:115], v[114:115], v[118:119]
	v_cvt_pk_bf16_f32 v146, v112, v113
	v_cvt_pk_bf16_f32 v147, v114, v115
	s_nop 1
	v_permlane32_swap_b32_e32 v144, v146
	v_permlane32_swap_b32_e32 v145, v147
	s_nop 1
	v_permlane16_swap_b32_e32 v144, v146
	v_permlane16_swap_b32_e32 v145, v147
	global_store_dwordx4 v131, v[144:147], s[66:67]
	v_add_u32_e32 v131, 0x16000, v130
	v_pk_mul_f32 v[132:133], v[104:105], s[2:3]
	v_pk_mul_f32 v[134:135], v[106:107], s[2:3]
	v_exp_f32_e32 v132, v132
	v_exp_f32_e32 v133, v133
	v_exp_f32_e32 v134, v134
	v_exp_f32_e32 v135, v135
	v_pk_mul_f32 v[136:137], v[96:97], s[2:3]
	v_pk_mul_f32 v[138:139], v[98:99], s[2:3]
	v_exp_f32_e32 v136, v136
	v_exp_f32_e32 v137, v137
	v_exp_f32_e32 v138, v138
	v_exp_f32_e32 v139, v139
	v_pk_add_f32 v[132:133], v[132:133], s[28:29]
	v_pk_add_f32 v[134:135], v[134:135], s[28:29]
	v_rcp_f32_e32 v132, v132
	v_rcp_f32_e32 v133, v133
	v_rcp_f32_e32 v134, v134
	v_rcp_f32_e32 v135, v135
	v_pk_add_f32 v[136:137], v[136:137], s[28:29]
	v_pk_add_f32 v[138:139], v[138:139], s[28:29]
	v_rcp_f32_e32 v136, v136
	v_rcp_f32_e32 v137, v137
	v_rcp_f32_e32 v138, v138
	v_rcp_f32_e32 v139, v139
	v_pk_mul_f32 v[104:105], v[104:105], v[132:133]
	v_pk_mul_f32 v[106:107], v[106:107], v[134:135]
	v_pk_mul_f32 v[104:105], v[104:105], v[108:109]
	v_pk_mul_f32 v[106:107], v[106:107], v[110:111]
	v_cvt_pk_bf16_f32 v148, v104, v105
	v_cvt_pk_bf16_f32 v149, v106, v107
	v_pk_mul_f32 v[96:97], v[96:97], v[136:137]
	v_pk_mul_f32 v[98:99], v[98:99], v[138:139]
	v_pk_mul_f32 v[96:97], v[96:97], v[100:101]
	v_pk_mul_f32 v[98:99], v[98:99], v[102:103]
	v_cvt_pk_bf16_f32 v150, v96, v97
	v_cvt_pk_bf16_f32 v151, v98, v99
	s_nop 1
	v_permlane32_swap_b32_e32 v148, v150
	v_permlane32_swap_b32_e32 v149, v151
	s_nop 1
	v_permlane16_swap_b32_e32 v148, v150
	v_permlane16_swap_b32_e32 v149, v151
	global_store_dwordx4 v131, v[148:151], s[66:67]
	v_add_u32_e32 v131, 0x2c000, v130
	v_pk_mul_f32 v[132:133], v[88:89], s[2:3]
	v_pk_mul_f32 v[134:135], v[90:91], s[2:3]
	v_exp_f32_e32 v132, v132
	v_exp_f32_e32 v133, v133
	v_exp_f32_e32 v134, v134
	v_exp_f32_e32 v135, v135
	v_pk_mul_f32 v[136:137], v[80:81], s[2:3]
	v_pk_mul_f32 v[138:139], v[82:83], s[2:3]
	v_exp_f32_e32 v136, v136
	v_exp_f32_e32 v137, v137
	v_exp_f32_e32 v138, v138
	v_exp_f32_e32 v139, v139
	v_pk_add_f32 v[132:133], v[132:133], s[28:29]
	v_pk_add_f32 v[134:135], v[134:135], s[28:29]
	v_rcp_f32_e32 v132, v132
	v_rcp_f32_e32 v133, v133
	v_rcp_f32_e32 v134, v134
	v_rcp_f32_e32 v135, v135
	v_pk_add_f32 v[136:137], v[136:137], s[28:29]
	v_pk_add_f32 v[138:139], v[138:139], s[28:29]
	v_rcp_f32_e32 v136, v136
	v_rcp_f32_e32 v137, v137
	v_rcp_f32_e32 v138, v138
	v_rcp_f32_e32 v139, v139
	v_pk_mul_f32 v[88:89], v[88:89], v[132:133]
	v_pk_mul_f32 v[90:91], v[90:91], v[134:135]
	v_pk_mul_f32 v[88:89], v[88:89], v[92:93]
	v_pk_mul_f32 v[90:91], v[90:91], v[94:95]
	v_cvt_pk_bf16_f32 v144, v88, v89
	v_cvt_pk_bf16_f32 v145, v90, v91
	v_pk_mul_f32 v[80:81], v[80:81], v[136:137]
	v_pk_mul_f32 v[82:83], v[82:83], v[138:139]
	v_pk_mul_f32 v[80:81], v[80:81], v[84:85]
	v_pk_mul_f32 v[82:83], v[82:83], v[86:87]
	v_cvt_pk_bf16_f32 v146, v80, v81
	v_cvt_pk_bf16_f32 v147, v82, v83
	s_nop 1
	v_permlane32_swap_b32_e32 v144, v146
	v_permlane32_swap_b32_e32 v145, v147
	s_nop 1
	v_permlane16_swap_b32_e32 v144, v146
	v_permlane16_swap_b32_e32 v145, v147
	global_store_dwordx4 v131, v[144:147], s[66:67]
	v_add_u32_e32 v131, 0x42000, v130
	v_pk_mul_f32 v[132:133], v[72:73], s[2:3]
	v_pk_mul_f32 v[134:135], v[74:75], s[2:3]
	v_exp_f32_e32 v132, v132
	v_exp_f32_e32 v133, v133
	v_exp_f32_e32 v134, v134
	v_exp_f32_e32 v135, v135
	v_pk_mul_f32 v[136:137], v[64:65], s[2:3]
	v_pk_mul_f32 v[138:139], v[66:67], s[2:3]
	v_exp_f32_e32 v136, v136
	v_exp_f32_e32 v137, v137
	v_exp_f32_e32 v138, v138
	v_exp_f32_e32 v139, v139
	v_pk_add_f32 v[132:133], v[132:133], s[28:29]
	v_pk_add_f32 v[134:135], v[134:135], s[28:29]
	v_rcp_f32_e32 v132, v132
	v_rcp_f32_e32 v133, v133
	v_rcp_f32_e32 v134, v134
	v_rcp_f32_e32 v135, v135
	v_pk_add_f32 v[136:137], v[136:137], s[28:29]
	v_pk_add_f32 v[138:139], v[138:139], s[28:29]
	v_rcp_f32_e32 v136, v136
	v_rcp_f32_e32 v137, v137
	v_rcp_f32_e32 v138, v138
	v_rcp_f32_e32 v139, v139
	v_pk_mul_f32 v[72:73], v[72:73], v[132:133]
	v_pk_mul_f32 v[74:75], v[74:75], v[134:135]
	v_pk_mul_f32 v[72:73], v[72:73], v[76:77]
	v_pk_mul_f32 v[74:75], v[74:75], v[78:79]
	v_cvt_pk_bf16_f32 v148, v72, v73
	v_cvt_pk_bf16_f32 v149, v74, v75
	v_pk_mul_f32 v[64:65], v[64:65], v[136:137]
	v_pk_mul_f32 v[66:67], v[66:67], v[138:139]
	v_pk_mul_f32 v[64:65], v[64:65], v[68:69]
	v_pk_mul_f32 v[66:67], v[66:67], v[70:71]
	v_cvt_pk_bf16_f32 v150, v64, v65
	v_cvt_pk_bf16_f32 v151, v66, v67
	s_nop 1
	v_permlane32_swap_b32_e32 v148, v150
	v_permlane32_swap_b32_e32 v149, v151
	s_nop 1
	v_permlane16_swap_b32_e32 v148, v150
	v_permlane16_swap_b32_e32 v149, v151
	global_store_dwordx4 v131, v[148:151], s[66:67]
	v_add_u32_e32 v131, 0xb0000, v130
	v_pk_mul_f32 v[132:133], v[56:57], s[2:3]
	v_pk_mul_f32 v[134:135], v[58:59], s[2:3]
	v_exp_f32_e32 v132, v132
	v_exp_f32_e32 v133, v133
	v_exp_f32_e32 v134, v134
	v_exp_f32_e32 v135, v135
	v_pk_mul_f32 v[136:137], v[48:49], s[2:3]
	v_pk_mul_f32 v[138:139], v[50:51], s[2:3]
	v_exp_f32_e32 v136, v136
	v_exp_f32_e32 v137, v137
	v_exp_f32_e32 v138, v138
	v_exp_f32_e32 v139, v139
	v_pk_add_f32 v[132:133], v[132:133], s[28:29]
	v_pk_add_f32 v[134:135], v[134:135], s[28:29]
	v_rcp_f32_e32 v132, v132
	v_rcp_f32_e32 v133, v133
	v_rcp_f32_e32 v134, v134
	v_rcp_f32_e32 v135, v135
	v_pk_add_f32 v[136:137], v[136:137], s[28:29]
	v_pk_add_f32 v[138:139], v[138:139], s[28:29]
	v_rcp_f32_e32 v136, v136
	v_rcp_f32_e32 v137, v137
	v_rcp_f32_e32 v138, v138
	v_rcp_f32_e32 v139, v139
	v_pk_mul_f32 v[56:57], v[56:57], v[132:133]
	v_pk_mul_f32 v[58:59], v[58:59], v[134:135]
	v_pk_mul_f32 v[56:57], v[56:57], v[60:61]
	v_pk_mul_f32 v[58:59], v[58:59], v[62:63]
	v_cvt_pk_bf16_f32 v144, v56, v57
	v_cvt_pk_bf16_f32 v145, v58, v59
	v_pk_mul_f32 v[48:49], v[48:49], v[136:137]
	v_pk_mul_f32 v[50:51], v[50:51], v[138:139]
	v_pk_mul_f32 v[48:49], v[48:49], v[52:53]
	v_pk_mul_f32 v[50:51], v[50:51], v[54:55]
	v_cvt_pk_bf16_f32 v146, v48, v49
	v_cvt_pk_bf16_f32 v147, v50, v51
	s_nop 1
	v_permlane32_swap_b32_e32 v144, v146
	v_permlane32_swap_b32_e32 v145, v147
	s_nop 1
	v_permlane16_swap_b32_e32 v144, v146
	v_permlane16_swap_b32_e32 v145, v147
	global_store_dwordx4 v131, v[144:147], s[66:67]
	v_add_u32_e32 v131, 0xc6000, v130
	v_pk_mul_f32 v[132:133], v[40:41], s[2:3]
	v_pk_mul_f32 v[134:135], v[42:43], s[2:3]
	v_exp_f32_e32 v132, v132
	v_exp_f32_e32 v133, v133
	v_exp_f32_e32 v134, v134
	v_exp_f32_e32 v135, v135
	v_pk_mul_f32 v[136:137], v[32:33], s[2:3]
	v_pk_mul_f32 v[138:139], v[34:35], s[2:3]
	v_exp_f32_e32 v136, v136
	v_exp_f32_e32 v137, v137
	v_exp_f32_e32 v138, v138
	v_exp_f32_e32 v139, v139
	v_pk_add_f32 v[132:133], v[132:133], s[28:29]
	v_pk_add_f32 v[134:135], v[134:135], s[28:29]
	v_rcp_f32_e32 v132, v132
	v_rcp_f32_e32 v133, v133
	v_rcp_f32_e32 v134, v134
	v_rcp_f32_e32 v135, v135
	v_pk_add_f32 v[136:137], v[136:137], s[28:29]
	v_pk_add_f32 v[138:139], v[138:139], s[28:29]
	v_rcp_f32_e32 v136, v136
	v_rcp_f32_e32 v137, v137
	v_rcp_f32_e32 v138, v138
	v_rcp_f32_e32 v139, v139
	v_pk_mul_f32 v[40:41], v[40:41], v[132:133]
	v_pk_mul_f32 v[42:43], v[42:43], v[134:135]
	v_pk_mul_f32 v[40:41], v[40:41], v[44:45]
	v_pk_mul_f32 v[42:43], v[42:43], v[46:47]
	v_cvt_pk_bf16_f32 v148, v40, v41
	v_cvt_pk_bf16_f32 v149, v42, v43
	v_pk_mul_f32 v[32:33], v[32:33], v[136:137]
	v_pk_mul_f32 v[34:35], v[34:35], v[138:139]
	v_pk_mul_f32 v[32:33], v[32:33], v[36:37]
	v_pk_mul_f32 v[34:35], v[34:35], v[38:39]
	v_cvt_pk_bf16_f32 v150, v32, v33
	v_cvt_pk_bf16_f32 v151, v34, v35
	s_nop 1
	v_permlane32_swap_b32_e32 v148, v150
	v_permlane32_swap_b32_e32 v149, v151
	s_nop 1
	v_permlane16_swap_b32_e32 v148, v150
	v_permlane16_swap_b32_e32 v149, v151
	global_store_dwordx4 v131, v[148:151], s[66:67]
	v_add_u32_e32 v131, 0xdc000, v130
	v_pk_mul_f32 v[132:133], v[24:25], s[2:3]
	v_pk_mul_f32 v[134:135], v[26:27], s[2:3]
	v_exp_f32_e32 v132, v132
	v_exp_f32_e32 v133, v133
	v_exp_f32_e32 v134, v134
	v_exp_f32_e32 v135, v135
	v_pk_mul_f32 v[136:137], v[16:17], s[2:3]
	v_pk_mul_f32 v[138:139], v[18:19], s[2:3]
	v_exp_f32_e32 v136, v136
	v_exp_f32_e32 v137, v137
	v_exp_f32_e32 v138, v138
	v_exp_f32_e32 v139, v139
	v_pk_add_f32 v[132:133], v[132:133], s[28:29]
	v_pk_add_f32 v[134:135], v[134:135], s[28:29]
	v_rcp_f32_e32 v132, v132
	v_rcp_f32_e32 v133, v133
	v_rcp_f32_e32 v134, v134
	v_rcp_f32_e32 v135, v135
	v_pk_add_f32 v[136:137], v[136:137], s[28:29]
	v_pk_add_f32 v[138:139], v[138:139], s[28:29]
	v_rcp_f32_e32 v136, v136
	v_rcp_f32_e32 v137, v137
	v_rcp_f32_e32 v138, v138
	v_rcp_f32_e32 v139, v139
	v_pk_mul_f32 v[24:25], v[24:25], v[132:133]
	v_pk_mul_f32 v[26:27], v[26:27], v[134:135]
	v_pk_mul_f32 v[24:25], v[24:25], v[28:29]
	v_pk_mul_f32 v[26:27], v[26:27], v[30:31]
	v_cvt_pk_bf16_f32 v144, v24, v25
	v_cvt_pk_bf16_f32 v145, v26, v27
	v_pk_mul_f32 v[16:17], v[16:17], v[136:137]
	v_pk_mul_f32 v[18:19], v[18:19], v[138:139]
	v_pk_mul_f32 v[16:17], v[16:17], v[20:21]
	v_pk_mul_f32 v[18:19], v[18:19], v[22:23]
	v_cvt_pk_bf16_f32 v146, v16, v17
	v_cvt_pk_bf16_f32 v147, v18, v19
	s_nop 1
	v_permlane32_swap_b32_e32 v144, v146
	v_permlane32_swap_b32_e32 v145, v147
	s_nop 1
	v_permlane16_swap_b32_e32 v144, v146
	v_permlane16_swap_b32_e32 v145, v147
	global_store_dwordx4 v131, v[144:147], s[66:67]
	v_add_u32_e32 v131, 0xf2000, v130
	v_pk_mul_f32 v[132:133], v[8:9], s[2:3]
	v_pk_mul_f32 v[134:135], v[10:11], s[2:3]
	v_exp_f32_e32 v132, v132
	v_exp_f32_e32 v133, v133
	v_exp_f32_e32 v134, v134
	v_exp_f32_e32 v135, v135
	v_pk_mul_f32 v[136:137], v[0:1], s[2:3]
	v_pk_mul_f32 v[138:139], v[2:3], s[2:3]
	v_exp_f32_e32 v136, v136
	v_exp_f32_e32 v137, v137
	v_exp_f32_e32 v138, v138
	v_exp_f32_e32 v139, v139
	v_pk_add_f32 v[132:133], v[132:133], s[28:29]
	v_pk_add_f32 v[134:135], v[134:135], s[28:29]
	v_rcp_f32_e32 v132, v132
	v_rcp_f32_e32 v133, v133
	v_rcp_f32_e32 v134, v134
	v_rcp_f32_e32 v135, v135
	v_pk_add_f32 v[136:137], v[136:137], s[28:29]
	v_pk_add_f32 v[138:139], v[138:139], s[28:29]
	v_rcp_f32_e32 v136, v136
	v_rcp_f32_e32 v137, v137
	v_rcp_f32_e32 v138, v138
	v_rcp_f32_e32 v139, v139
	v_pk_mul_f32 v[8:9], v[8:9], v[132:133]
	v_pk_mul_f32 v[10:11], v[10:11], v[134:135]
	v_pk_mul_f32 v[8:9], v[8:9], v[12:13]
	v_pk_mul_f32 v[10:11], v[10:11], v[14:15]
	v_cvt_pk_bf16_f32 v148, v8, v9
	v_cvt_pk_bf16_f32 v149, v10, v11
	v_pk_mul_f32 v[0:1], v[0:1], v[136:137]
	v_pk_mul_f32 v[2:3], v[2:3], v[138:139]
	v_pk_mul_f32 v[0:1], v[0:1], v[4:5]
	v_pk_mul_f32 v[2:3], v[2:3], v[6:7]
	v_cvt_pk_bf16_f32 v150, v0, v1
	v_cvt_pk_bf16_f32 v151, v2, v3
	s_nop 1
	v_permlane32_swap_b32_e32 v148, v150
	v_permlane32_swap_b32_e32 v149, v151
	s_nop 1
	v_permlane16_swap_b32_e32 v148, v150
	v_permlane16_swap_b32_e32 v149, v151
	global_store_dwordx4 v131, v[148:151], s[66:67]
	s_add_i32 s11, s11, s10
	s_cmpk_gt_i32 s11, 0x5ab
	s_waitcnt vmcnt(0)
	s_cbranch_scc1 .LBB0_335

.LBB0_992:
	v_lshl_add_u32 v34, v212, 2, s33
	ds_read2st64_b32 v[32:33], v34 offset0:204 offset1:206
	v_mul_u32_u24_e32 v36, 0x1100, v213
	v_or_b32_e32 v37, v36, v212
	v_lshl_add_u32 v37, v37, 1, s33
	v_lshlrev_b32_e32 v38, 1, v212
	s_waitcnt lgkmcnt(0)
	v_mul_f32_e32 v35, v32, v58
	v_cvt_pk_bf16_f32 v35, v35, s0
	ds_write_b16 v37, v35
	v_mul_f32_e32 v35, v58, v33
	v_sub_u32_e32 v34, v34, v38
	v_cvt_pk_bf16_f32 v35, v35, s0
	v_lshl_add_u32 v34, v36, 1, v34
	ds_write_b16 v34, v35 offset:17408
	v_mul_f32_e32 v35, v32, v59
	v_cvt_pk_bf16_f32 v35, v35, s0
	ds_write_b16 v34, v35 offset:272
	v_mul_f32_e32 v35, v59, v33
	v_cvt_pk_bf16_f32 v35, v35, s0
	ds_write_b16 v34, v35 offset:17680
	v_mul_f32_e32 v35, v32, v88
	v_cvt_pk_bf16_f32 v35, v35, s0
	ds_write_b16 v34, v35 offset:544
	v_mul_f32_e32 v35, v88, v33
	v_cvt_pk_bf16_f32 v35, v35, s0
	ds_write_b16 v34, v35 offset:17952
	v_mul_f32_e32 v35, v32, v89
	v_cvt_pk_bf16_f32 v35, v35, s0
	ds_write_b16 v34, v35 offset:816
	v_mul_f32_e32 v35, v89, v33
	v_cvt_pk_bf16_f32 v35, v35, s0
	ds_write_b16 v34, v35 offset:18224
	v_mul_f32_e32 v35, v32, v78
	v_cvt_pk_bf16_f32 v35, v35, s0
	ds_write_b16 v34, v35 offset:1088
	v_mul_f32_e32 v35, v78, v33
	v_cvt_pk_bf16_f32 v35, v35, s0
	ds_write_b16 v34, v35 offset:18496
	v_mul_f32_e32 v35, v32, v79
	v_cvt_pk_bf16_f32 v35, v35, s0
	ds_write_b16 v34, v35 offset:1360
	v_mul_f32_e32 v35, v79, v33
	v_cvt_pk_bf16_f32 v35, v35, s0
	ds_write_b16 v34, v35 offset:18768
	v_mul_f32_e32 v35, v32, v76
	v_cvt_pk_bf16_f32 v35, v35, s0
	ds_write_b16 v34, v35 offset:1632
	v_mul_f32_e32 v35, v76, v33
	v_cvt_pk_bf16_f32 v35, v35, s0
	ds_write_b16 v34, v35 offset:19040
	v_mul_f32_e32 v35, v32, v77
	v_cvt_pk_bf16_f32 v35, v35, s0
	ds_write_b16 v34, v35 offset:1904
	v_mul_f32_e32 v35, v77, v33
	v_cvt_pk_bf16_f32 v35, v35, s0
	ds_write_b16 v34, v35 offset:19312
	v_mul_f32_e32 v35, v32, v80
	v_cvt_pk_bf16_f32 v35, v35, s0
	ds_write_b16 v34, v35 offset:2176
	v_mul_f32_e32 v35, v80, v33
	v_cvt_pk_bf16_f32 v35, v35, s0
	ds_write_b16 v34, v35 offset:19584
	v_mul_f32_e32 v35, v32, v81
	v_cvt_pk_bf16_f32 v35, v35, s0
	ds_write_b16 v34, v35 offset:2448
	v_mul_f32_e32 v35, v81, v33
	v_cvt_pk_bf16_f32 v35, v35, s0
	ds_write_b16 v34, v35 offset:19856
	v_mul_f32_e32 v35, v32, v84
	v_cvt_pk_bf16_f32 v35, v35, s0
	ds_write_b16 v34, v35 offset:2720
	v_mul_f32_e32 v35, v84, v33
	v_cvt_pk_bf16_f32 v35, v35, s0
	ds_write_b16 v34, v35 offset:20128
	v_mul_f32_e32 v35, v32, v85
	v_cvt_pk_bf16_f32 v35, v35, s0
	ds_write_b16 v34, v35 offset:2992
	v_mul_f32_e32 v35, v85, v33
	v_cvt_pk_bf16_f32 v35, v35, s0
	ds_write_b16 v34, v35 offset:20400
	v_mul_f32_e32 v35, v32, v82
	v_cvt_pk_bf16_f32 v35, v35, s0
	ds_write_b16 v34, v35 offset:3264
	v_mul_f32_e32 v35, v82, v33
	v_cvt_pk_bf16_f32 v35, v35, s0
	ds_write_b16 v34, v35 offset:20672
	v_mul_f32_e32 v35, v32, v83
	v_cvt_pk_bf16_f32 v35, v35, s0
	ds_write_b16 v34, v35 offset:3536
	v_mul_f32_e32 v35, v83, v33
	v_cvt_pk_bf16_f32 v35, v35, s0
	ds_write_b16 v34, v35 offset:20944
	v_mul_f32_e32 v35, v32, v56
	v_cvt_pk_bf16_f32 v35, v35, s0
	ds_write_b16 v34, v35 offset:3808
	v_mul_f32_e32 v35, v56, v33
	v_cvt_pk_bf16_f32 v35, v35, s0
	ds_write_b16 v34, v35 offset:21216
	v_mul_f32_e32 v35, v32, v57
	v_cvt_pk_bf16_f32 v35, v35, s0
	ds_write_b16 v34, v35 offset:4080
	v_mul_f32_e32 v35, v57, v33
	v_cvt_pk_bf16_f32 v35, v35, s0
	ds_write_b16 v34, v35 offset:21488
	v_mul_f32_e32 v35, v32, v18
	v_mul_f32_e32 v18, v18, v33
	v_cvt_pk_bf16_f32 v18, v18, s0
	ds_write_b16 v34, v18 offset:21760
	v_mul_f32_e32 v18, v32, v19
	v_cvt_pk_bf16_f32 v18, v18, s0
	ds_write_b16 v34, v18 offset:4624
	v_mul_f32_e32 v18, v19, v33
	v_cvt_pk_bf16_f32 v18, v18, s0
	ds_write_b16 v34, v18 offset:22032
	v_mul_f32_e32 v18, v32, v26
	v_cvt_pk_bf16_f32 v18, v18, s0
	ds_write_b16 v34, v18 offset:4896
	v_mul_f32_e32 v18, v26, v33
	v_cvt_pk_bf16_f32 v18, v18, s0
	ds_write_b16 v34, v18 offset:22304
	v_mul_f32_e32 v18, v32, v27
	v_cvt_pk_bf16_f32 v18, v18, s0
	ds_write_b16 v34, v18 offset:5168
	v_mul_f32_e32 v18, v27, v33
	v_cvt_pk_bf16_f32 v18, v18, s0
	ds_write_b16 v34, v18 offset:22576
	v_mul_f32_e32 v18, v32, v24
	v_cvt_pk_bf16_f32 v18, v18, s0
	ds_write_b16 v34, v18 offset:5440
	v_mul_f32_e32 v18, v24, v33
	v_cvt_pk_bf16_f32 v18, v18, s0
	ds_write_b16 v34, v18 offset:22848
	v_mul_f32_e32 v18, v32, v25
	v_cvt_pk_bf16_f32 v18, v18, s0
	ds_write_b16 v34, v18 offset:5712
	v_mul_f32_e32 v18, v25, v33
	v_cvt_pk_bf16_f32 v18, v18, s0
	ds_write_b16 v34, v18 offset:23120
	v_mul_f32_e32 v18, v32, v16
	v_mul_f32_e32 v16, v16, v33
	v_cvt_pk_bf16_f32 v16, v16, s0
	ds_write_b16 v34, v16 offset:23392
	v_mul_f32_e32 v16, v32, v17
	v_cvt_pk_bf16_f32 v16, v16, s0
	ds_write_b16 v34, v16 offset:6256
	v_mul_f32_e32 v16, v17, v33
	v_cvt_pk_bf16_f32 v16, v16, s0
	ds_write_b16 v34, v16 offset:23664
	v_mul_f32_e32 v16, v32, v20
	v_cvt_pk_bf16_f32 v16, v16, s0
	ds_write_b16 v34, v16 offset:6528
	v_mul_f32_e32 v16, v20, v33
	v_cvt_pk_bf16_f32 v16, v16, s0
	ds_write_b16 v34, v16 offset:23936
	v_mul_f32_e32 v16, v32, v21
	v_cvt_pk_bf16_f32 v16, v16, s0
	ds_write_b16 v34, v16 offset:6800
	v_mul_f32_e32 v16, v21, v33
	v_cvt_pk_bf16_f32 v16, v16, s0
	ds_write_b16 v34, v16 offset:24208
	v_mul_f32_e32 v16, v32, v22
	v_cvt_pk_bf16_f32 v16, v16, s0
	ds_write_b16 v34, v16 offset:7072
	v_mul_f32_e32 v16, v22, v33
	v_cvt_pk_bf16_f32 v16, v16, s0
	ds_write_b16 v34, v16 offset:24480
	v_mul_f32_e32 v16, v32, v23
	v_cvt_pk_bf16_f32 v16, v16, s0
	ds_write_b16 v34, v16 offset:7344
	v_mul_f32_e32 v16, v23, v33
	v_cvt_pk_bf16_f32 v16, v16, s0
	ds_write_b16 v34, v16 offset:24752
	v_mul_f32_e32 v16, v32, v28
	v_cvt_pk_bf16_f32 v16, v16, s0
	ds_write_b16 v34, v16 offset:7616
	v_mul_f32_e32 v16, v28, v33
	v_cvt_pk_bf16_f32 v16, v16, s0
	ds_write_b16 v34, v16 offset:25024
	v_mul_f32_e32 v16, v32, v29
	v_cvt_pk_bf16_f32 v16, v16, s0
	ds_write_b16 v34, v16 offset:7888
	v_mul_f32_e32 v16, v29, v33
	v_cvt_pk_bf16_f32 v16, v16, s0
	ds_write_b16 v34, v16 offset:25296
	v_mul_f32_e32 v16, v32, v30
	v_cvt_pk_bf16_f32 v16, v16, s0
	ds_write_b16 v34, v16 offset:8160
	v_mul_f32_e32 v16, v30, v33
	v_mul_f32_e32 v31, 0x3e000000, v45
	v_cvt_pk_bf16_f32 v16, v16, s0
	ds_write_b16 v34, v16 offset:25568
	v_mul_f32_e32 v16, v31, v32
	v_cvt_pk_bf16_f32 v16, v16, s0
	ds_write_b16 v34, v16 offset:8432
	v_mul_f32_e32 v16, v31, v33
	v_cvt_pk_bf16_f32 v35, v35, s0
	v_cvt_pk_bf16_f32 v18, v18, s0
	v_cvt_pk_bf16_f32 v16, v16, s0
	ds_write_b16 v34, v35 offset:4352
	ds_write_b16 v34, v18 offset:5984
	ds_write_b16 v34, v16 offset:25840
	s_waitcnt vmcnt(0)
	ds_write_b16 v37, v12 offset:34816
	ds_write_b16_d16_hi v34, v12 offset:35088
	ds_write_b16 v34, v13 offset:35360
	ds_write_b16_d16_hi v34, v13 offset:35632
	ds_write_b16 v34, v14 offset:35904
	ds_write_b16_d16_hi v34, v14 offset:36176
	ds_write_b16 v34, v15 offset:36448
	ds_write_b16_d16_hi v34, v15 offset:36720
	ds_write_b16 v34, v8 offset:36992
	ds_write_b16_d16_hi v34, v8 offset:37264
	ds_write_b16 v34, v9 offset:37536
	ds_write_b16_d16_hi v34, v9 offset:37808
	ds_write_b16 v34, v10 offset:38080
	ds_write_b16_d16_hi v34, v10 offset:38352
	ds_write_b16 v34, v11 offset:38624
	ds_write_b16_d16_hi v34, v11 offset:38896
	ds_write_b16 v34, v4 offset:39168
	ds_write_b16_d16_hi v34, v4 offset:39440
	ds_write_b16 v34, v5 offset:39712
	ds_write_b16_d16_hi v34, v5 offset:39984
	ds_write_b16 v34, v6 offset:40256
	ds_write_b16_d16_hi v34, v6 offset:40528
	ds_write_b16 v34, v7 offset:40800
	ds_write_b16_d16_hi v34, v7 offset:41072
	ds_write_b16 v34, v0 offset:41344
	ds_write_b16_d16_hi v34, v0 offset:41616
	ds_write_b16 v34, v1 offset:41888
	ds_write_b16_d16_hi v34, v1 offset:42160
	ds_write_b16 v34, v2 offset:42432
	ds_write_b16_d16_hi v34, v2 offset:42704
	ds_write_b16 v34, v3 offset:42976
	ds_write_b16_d16_hi v34, v3 offset:43248
	v_lshrrev_b32_e32 v3, 2, v211
	v_bfe_u32 v0, v209, 6, 1
	v_and_b32_e32 v1, 31, v211
	v_and_b32_e32 v3, 32, v3
	v_or_b32_e32 v4, v3, v1
	v_lshl_or_b32 v5, v0, 5, v1
	v_lshlrev_b32_e32 v1, 7, v1
	v_lshl_or_b32 v160, v0, 12, v1
	s_bfe_u32 s1, s38, 0x10003
	v_lshrrev_b32_e32 v2, 5, v208
	v_lshl_add_u64 v[0:1], s[20:21], 0, v[160:161]
	v_lshlrev_b32_e32 v160, 1, v3
	s_and_b64 s[2:3], s[26:27], exec
	v_lshl_add_u64 v[0:1], v[0:1], 0, v[160:161]
	v_lshlrev_b32_e32 v160, 3, v2
	v_lshl_add_u64 v[24:25], v[0:1], 0, v[160:161]
	v_lshl_add_u32 v0, v2, 4, s33
	s_movk_i32 s2, 0x110
	v_mad_u32_u24 v54, v4, s2, v0
	s_waitcnt lgkmcnt(0)
	s_barrier
	v_mad_u32_u24 v55, v5, s2, v0
	ds_read_b128 v[0:3], v54
	ds_read_b128 v[16:19], v54 offset:32
	ds_read_b128 v[26:29], v55 offset:34816
	ds_read_b128 v[30:33], v55 offset:34848
	s_waitcnt lgkmcnt(1)
	v_mfma_f32_32x32x16_bf16 v[0:15], v[0:3], v[26:29], 0
	s_cselect_b32 s0, 0x43, 1
	s_lshl_b32 s2, s1, 5
	s_lshl_b32 s3, s36, 3
	s_add_i32 s2, s2, s3
	s_or_b32 s2, s2, s37
	s_sub_i32 s0, s0, s35
	s_mul_i32 s3, s2, 0x42
	s_waitcnt lgkmcnt(0)
	v_mfma_f32_32x32x16_bf16 v[0:15], v[16:19], v[30:33], v[0:15]
	ds_read_b128 v[16:19], v54 offset:64
	ds_read_b128 v[34:37], v55 offset:34880
	s_ashr_i32 s6, s35, 31
	s_mul_hi_i32 s5, s2, 0x42
	s_add_u32 s4, s3, s35
	s_addc_u32 s5, s5, s6
	s_lshl_b64 s[4:5], s[4:5], 13
	s_add_i32 s2, s2, 16
	s_waitcnt lgkmcnt(0)
	v_mfma_f32_32x32x16_bf16 v[0:15], v[16:19], v[34:37], v[0:15]
	ds_read_b128 v[16:19], v54 offset:96
	ds_read_b128 v[38:41], v55 offset:34912
	s_addk_i32 s3, 0x420
	s_waitcnt lgkmcnt(0)
	v_mfma_f32_32x32x16_bf16 v[0:15], v[16:19], v[38:41], v[0:15]
	ds_read_b128 v[16:19], v54 offset:128
	ds_read_b128 v[42:45], v55 offset:34944
	s_waitcnt lgkmcnt(0)
	v_mfma_f32_32x32x16_bf16 v[0:15], v[16:19], v[42:45], v[0:15]
	ds_read_b128 v[16:19], v54 offset:160
	ds_read_b128 v[46:49], v55 offset:34976
	s_waitcnt lgkmcnt(0)
	v_mfma_f32_32x32x16_bf16 v[0:15], v[16:19], v[46:49], v[0:15]
	ds_read_b128 v[16:19], v54 offset:192
	ds_read_b128 v[20:23], v55 offset:35008
	s_waitcnt lgkmcnt(0)
	v_mfma_f32_32x32x16_bf16 v[0:15], v[16:19], v[20:23], v[0:15]
	ds_read_b128 v[50:53], v54 offset:224
	ds_read_b128 v[16:19], v55 offset:35040
	s_waitcnt lgkmcnt(0)
	v_mfma_f32_32x32x16_bf16 v[0:15], v[50:53], v[16:19], v[0:15]
	v_lshl_add_u64 v[50:51], v[24:25], 0, s[4:5]
	s_mul_hi_i32 s4, s2, 0x42
	s_add_u32 s2, s3, s0
	s_addc_u32 s3, s4, 0
	s_lshl_b64 s[2:3], s[2:3], 13
	s_cmp_lg_u32 s1, 0
	s_movk_i32 s1, 0x80
	s_nop 4
	v_cvt_pk_bf16_f32 v0, v0, v1
	v_cvt_pk_bf16_f32 v1, v2, v3
	v_cvt_pk_bf16_f32 v2, v4, v5
	v_cvt_pk_bf16_f32 v3, v6, v7
	v_cvt_pk_bf16_f32 v4, v8, v9
	v_cvt_pk_bf16_f32 v5, v10, v11
	v_cvt_pk_bf16_f32 v6, v12, v13
	v_cvt_pk_bf16_f32 v7, v14, v15
	v_mbcnt_lo_u32_b32 v8, -1, 0
	v_mbcnt_hi_u32_b32 v8, -1, v8
	v_lshrrev_b32_e32 v8, 2, v8
	v_and_b32_e32 v8, 8, v8
	v_mov_b32_e32 v9, 0
	v_permlane32_swap_b32_e32 v0, v2
	v_permlane32_swap_b32_e32 v1, v3
	v_permlane32_swap_b32_e32 v4, v6
	v_permlane32_swap_b32_e32 v5, v7
	v_lshl_add_u64 v[50:51], v[50:51], 0, v[8:9]
	global_store_dwordx4 v[50:51], v[0:3], off
	global_store_dwordx4 v[50:51], v[4:7], off offset:32
	s_nop 1
	ds_read_b128 v[0:3], v54 offset:17408
	ds_read_b128 v[50:53], v54 offset:17440
	s_waitcnt lgkmcnt(1)
	v_mfma_f32_32x32x16_bf16 v[0:15], v[0:3], v[26:29], 0
	ds_read_b128 v[26:29], v54 offset:17472
	v_cmp_gt_u32_e32 vcc, s1, v209
	s_waitcnt lgkmcnt(1)
	v_mfma_f32_32x32x16_bf16 v[0:15], v[50:53], v[30:33], v[0:15]
	s_waitcnt lgkmcnt(0)
	v_mfma_f32_32x32x16_bf16 v[0:15], v[26:29], v[34:37], v[0:15]
	ds_read_b128 v[26:29], v54 offset:17504
	s_waitcnt lgkmcnt(0)
	v_mfma_f32_32x32x16_bf16 v[0:15], v[26:29], v[38:41], v[0:15]
	ds_read_b128 v[26:29], v54 offset:17536
	s_waitcnt lgkmcnt(0)
	v_mfma_f32_32x32x16_bf16 v[0:15], v[26:29], v[42:45], v[0:15]
	ds_read_b128 v[26:29], v54 offset:17568
	s_waitcnt lgkmcnt(0)
	v_mfma_f32_32x32x16_bf16 v[0:15], v[26:29], v[46:49], v[0:15]
	ds_read_b128 v[26:29], v54 offset:17600
	s_waitcnt lgkmcnt(0)
	v_mfma_f32_32x32x16_bf16 v[0:15], v[26:29], v[20:23], v[0:15]
	ds_read_b128 v[20:23], v54 offset:17632
	s_waitcnt lgkmcnt(0)
	v_mfma_f32_32x32x16_bf16 v[0:15], v[20:23], v[16:19], v[0:15]
	v_lshl_add_u64 v[16:17], v[24:25], 0, s[2:3]
	s_cselect_b64 s[2:3], -1, 0
	s_and_b64 s[2:3], s[2:3], vcc
	s_nop 8
	v_cvt_pk_bf16_f32 v0, v0, v1
	v_cvt_pk_bf16_f32 v1, v2, v3
	v_cvt_pk_bf16_f32 v2, v4, v5
	v_cvt_pk_bf16_f32 v3, v6, v7
	v_cvt_pk_bf16_f32 v4, v8, v9
	v_cvt_pk_bf16_f32 v5, v10, v11
	v_cvt_pk_bf16_f32 v6, v12, v13
	v_cvt_pk_bf16_f32 v7, v14, v15
	v_mbcnt_lo_u32_b32 v8, -1, 0
	v_mbcnt_hi_u32_b32 v8, -1, v8
	v_lshrrev_b32_e32 v8, 2, v8
	v_and_b32_e32 v8, 8, v8
	v_mov_b32_e32 v9, 0
	v_permlane32_swap_b32_e32 v0, v2
	v_permlane32_swap_b32_e32 v1, v3
	v_permlane32_swap_b32_e32 v4, v6
	v_permlane32_swap_b32_e32 v5, v7
	v_lshl_add_u64 v[16:17], v[16:17], 0, v[8:9]
	global_store_dwordx4 v[16:17], v[0:3], off
	global_store_dwordx4 v[16:17], v[4:7], off offset:32
	s_nop 1
	s_and_saveexec_b64 s[4:5], s[2:3]
	s_cbranch_execz .LBB0_958
	v_and_b32_e32 v0, 64, v211
	v_mul_u32_u24_e32 v0, 0x110, v0
	v_mul_u32_u24_e32 v1, 0x110, v208
	v_add3_u32 v16, s33, v0, v1
	ds_read_b128 v[0:3], v16
	ds_read_b128 v[4:7], v16 offset:16
	ds_read_b128 v[8:11], v16 offset:32
	ds_read_b128 v[12:15], v16 offset:48
	v_cmp_gt_u32_e32 vcc, 64, v209
	s_waitcnt lgkmcnt(3)
	v_lshlrev_b32_e32 v17, 16, v0
	v_and_b32_e32 v0, 0xffff0000, v0
	v_add_f32_e32 v17, 0, v17
	v_lshlrev_b32_e32 v18, 16, v1
	v_add_f32_e32 v0, v17, v0
	v_and_b32_e32 v1, 0xffff0000, v1
	v_add_f32_e32 v0, v0, v18
	v_lshlrev_b32_e32 v19, 16, v2
	v_add_f32_e32 v0, v0, v1
	v_and_b32_e32 v2, 0xffff0000, v2
	v_add_f32_e32 v0, v0, v19
	v_lshlrev_b32_e32 v20, 16, v3
	v_add_f32_e32 v0, v0, v2
	v_and_b32_e32 v3, 0xffff0000, v3
	v_add_f32_e32 v0, v0, v20
	v_add_f32_e32 v0, v0, v3
	s_waitcnt lgkmcnt(2)
	v_lshlrev_b32_e32 v1, 16, v4
	v_and_b32_e32 v2, 0xffff0000, v4
	v_add_f32_e32 v0, v0, v1
	v_lshlrev_b32_e32 v3, 16, v5
	v_add_f32_e32 v0, v0, v2
	v_and_b32_e32 v4, 0xffff0000, v5
	v_add_f32_e32 v0, v0, v3
	v_lshlrev_b32_e32 v5, 16, v6
	v_add_f32_e32 v0, v0, v4
	v_and_b32_e32 v6, 0xffff0000, v6
	v_add_f32_e32 v0, v0, v5
	v_lshlrev_b32_e32 v17, 16, v7
	v_add_f32_e32 v0, v0, v6
	v_and_b32_e32 v7, 0xffff0000, v7
	v_add_f32_e32 v0, v0, v17
	v_add_f32_e32 v0, v0, v7
	s_waitcnt lgkmcnt(1)
	v_lshlrev_b32_e32 v1, 16, v8
	v_and_b32_e32 v2, 0xffff0000, v8
	v_add_f32_e32 v0, v0, v1
	v_lshlrev_b32_e32 v3, 16, v9
	v_add_f32_e32 v0, v0, v2
	v_and_b32_e32 v4, 0xffff0000, v9
	v_add_f32_e32 v0, v0, v3
	v_lshlrev_b32_e32 v5, 16, v10
	v_add_f32_e32 v0, v0, v4
	v_and_b32_e32 v6, 0xffff0000, v10
	v_add_f32_e32 v0, v0, v5
	v_lshlrev_b32_e32 v7, 16, v11
	v_add_f32_e32 v0, v0, v6
	v_and_b32_e32 v8, 0xffff0000, v11
	v_add_f32_e32 v0, v0, v7
	v_add_f32_e32 v0, v0, v8
	s_waitcnt lgkmcnt(0)
	v_lshlrev_b32_e32 v1, 16, v12
	v_and_b32_e32 v2, 0xffff0000, v12
	v_add_f32_e32 v0, v0, v1
	v_lshlrev_b32_e32 v3, 16, v13
	v_add_f32_e32 v0, v0, v2
	v_and_b32_e32 v4, 0xffff0000, v13
	v_add_f32_e32 v0, v0, v3
	v_lshlrev_b32_e32 v5, 16, v14
	v_add_f32_e32 v0, v0, v4
	v_add_f32_e32 v4, v0, v5
	ds_read_b128 v[0:3], v16 offset:64
	v_and_b32_e32 v6, 0xffff0000, v14
	v_lshlrev_b32_e32 v7, 16, v15
	v_add_f32_e32 v4, v4, v6
	v_and_b32_e32 v8, 0xffff0000, v15
	v_add_f32_e32 v4, v4, v7
	v_add_f32_e32 v8, v4, v8
	ds_read_b128 v[4:7], v16 offset:80
	s_waitcnt lgkmcnt(1)
	v_lshlrev_b32_e32 v9, 16, v0
	v_and_b32_e32 v0, 0xffff0000, v0
	v_add_f32_e32 v8, v8, v9
	v_lshlrev_b32_e32 v10, 16, v1
	v_add_f32_e32 v0, v8, v0
	v_and_b32_e32 v1, 0xffff0000, v1
	v_add_f32_e32 v0, v0, v10
	v_lshlrev_b32_e32 v11, 16, v2
	v_add_f32_e32 v0, v0, v1
	v_and_b32_e32 v2, 0xffff0000, v2
	v_add_f32_e32 v0, v0, v11
	v_lshlrev_b32_e32 v12, 16, v3
	v_add_f32_e32 v0, v0, v2
	v_and_b32_e32 v3, 0xffff0000, v3
	v_add_f32_e32 v0, v0, v12
	v_add_f32_e32 v0, v0, v3
	s_waitcnt lgkmcnt(0)
	v_lshlrev_b32_e32 v1, 16, v4
	v_and_b32_e32 v2, 0xffff0000, v4
	v_add_f32_e32 v0, v0, v1
	v_lshlrev_b32_e32 v3, 16, v5
	v_add_f32_e32 v0, v0, v2
	v_and_b32_e32 v4, 0xffff0000, v5
	v_add_f32_e32 v0, v0, v3
	v_lshlrev_b32_e32 v5, 16, v6
	v_add_f32_e32 v0, v0, v4
	v_add_f32_e32 v4, v0, v5
	ds_read_b128 v[0:3], v16 offset:96
	v_and_b32_e32 v6, 0xffff0000, v6
	v_lshlrev_b32_e32 v8, 16, v7
	v_add_f32_e32 v4, v4, v6
	v_and_b32_e32 v7, 0xffff0000, v7
	v_add_f32_e32 v4, v4, v8
	v_add_f32_e32 v8, v4, v7
	ds_read_b128 v[4:7], v16 offset:112
	s_waitcnt lgkmcnt(1)
	v_lshlrev_b32_e32 v9, 16, v0
	v_and_b32_e32 v0, 0xffff0000, v0
	v_add_f32_e32 v8, v8, v9
	v_lshlrev_b32_e32 v10, 16, v1
	v_add_f32_e32 v0, v8, v0
	v_and_b32_e32 v1, 0xffff0000, v1
	v_add_f32_e32 v0, v0, v10
	v_lshlrev_b32_e32 v11, 16, v2
	v_add_f32_e32 v0, v0, v1
	v_and_b32_e32 v2, 0xffff0000, v2
	v_add_f32_e32 v0, v0, v11
	v_lshlrev_b32_e32 v12, 16, v3
	v_add_f32_e32 v0, v0, v2
	v_and_b32_e32 v3, 0xffff0000, v3
	v_add_f32_e32 v0, v0, v12
	v_add_f32_e32 v0, v0, v3
	s_waitcnt lgkmcnt(0)
	v_lshlrev_b32_e32 v1, 16, v4
	v_and_b32_e32 v2, 0xffff0000, v4
	v_add_f32_e32 v0, v0, v1
	v_lshlrev_b32_e32 v3, 16, v5
	v_add_f32_e32 v0, v0, v2
	v_and_b32_e32 v4, 0xffff0000, v5
	v_add_f32_e32 v0, v0, v3
	v_lshlrev_b32_e32 v5, 16, v6
	v_add_f32_e32 v0, v0, v4
	v_add_f32_e32 v4, v0, v5
	ds_read_b128 v[0:3], v16 offset:128
	v_and_b32_e32 v6, 0xffff0000, v6
	v_lshlrev_b32_e32 v8, 16, v7
	v_add_f32_e32 v4, v4, v6
	v_and_b32_e32 v7, 0xffff0000, v7
	v_add_f32_e32 v4, v4, v8
	v_add_f32_e32 v8, v4, v7
	ds_read_b128 v[4:7], v16 offset:144
	s_waitcnt lgkmcnt(1)
	v_lshlrev_b32_e32 v9, 16, v0
	v_and_b32_e32 v0, 0xffff0000, v0
	v_add_f32_e32 v8, v8, v9
	v_lshlrev_b32_e32 v10, 16, v1
	v_add_f32_e32 v0, v8, v0
	v_and_b32_e32 v1, 0xffff0000, v1
	v_add_f32_e32 v0, v0, v10
	v_lshlrev_b32_e32 v11, 16, v2
	v_add_f32_e32 v0, v0, v1
	v_and_b32_e32 v2, 0xffff0000, v2
	v_add_f32_e32 v0, v0, v11
	v_lshlrev_b32_e32 v12, 16, v3
	v_add_f32_e32 v0, v0, v2
	v_and_b32_e32 v3, 0xffff0000, v3
	v_add_f32_e32 v0, v0, v12
	v_add_f32_e32 v0, v0, v3
	s_waitcnt lgkmcnt(0)
	v_lshlrev_b32_e32 v1, 16, v4
	v_and_b32_e32 v2, 0xffff0000, v4
	v_add_f32_e32 v0, v0, v1
	v_lshlrev_b32_e32 v3, 16, v5
	v_add_f32_e32 v0, v0, v2
	v_and_b32_e32 v4, 0xffff0000, v5
	v_add_f32_e32 v0, v0, v3
	v_lshlrev_b32_e32 v5, 16, v6
	v_add_f32_e32 v0, v0, v4
	v_add_f32_e32 v4, v0, v5
	ds_read_b128 v[0:3], v16 offset:160
	v_and_b32_e32 v6, 0xffff0000, v6
	v_lshlrev_b32_e32 v8, 16, v7
	v_add_f32_e32 v4, v4, v6
	v_and_b32_e32 v7, 0xffff0000, v7
	v_add_f32_e32 v4, v4, v8
	v_add_f32_e32 v8, v4, v7
	ds_read_b128 v[4:7], v16 offset:176
	s_waitcnt lgkmcnt(1)
	v_lshlrev_b32_e32 v9, 16, v0
	v_and_b32_e32 v0, 0xffff0000, v0
	v_add_f32_e32 v8, v8, v9
	v_lshlrev_b32_e32 v10, 16, v1
	v_add_f32_e32 v0, v8, v0
	v_and_b32_e32 v1, 0xffff0000, v1
	v_add_f32_e32 v0, v0, v10
	v_lshlrev_b32_e32 v11, 16, v2
	v_add_f32_e32 v0, v0, v1
	v_and_b32_e32 v2, 0xffff0000, v2
	v_add_f32_e32 v0, v0, v11
	v_lshlrev_b32_e32 v12, 16, v3
	v_add_f32_e32 v0, v0, v2
	v_and_b32_e32 v3, 0xffff0000, v3
	v_add_f32_e32 v0, v0, v12
	v_add_f32_e32 v0, v0, v3
	s_waitcnt lgkmcnt(0)
	v_lshlrev_b32_e32 v1, 16, v4
	v_and_b32_e32 v2, 0xffff0000, v4
	v_add_f32_e32 v0, v0, v1
	v_lshlrev_b32_e32 v3, 16, v5
	v_add_f32_e32 v0, v0, v2
	v_and_b32_e32 v4, 0xffff0000, v5
	v_add_f32_e32 v0, v0, v3
	v_lshlrev_b32_e32 v5, 16, v6
	v_add_f32_e32 v0, v0, v4
	v_add_f32_e32 v4, v0, v5
	ds_read_b128 v[0:3], v16 offset:192
	v_and_b32_e32 v6, 0xffff0000, v6
	v_lshlrev_b32_e32 v8, 16, v7
	v_add_f32_e32 v4, v4, v6
	v_and_b32_e32 v7, 0xffff0000, v7
	v_add_f32_e32 v4, v4, v8
	v_add_f32_e32 v8, v4, v7
	ds_read_b128 v[4:7], v16 offset:208
	s_waitcnt lgkmcnt(1)
	v_lshlrev_b32_e32 v9, 16, v0
	v_and_b32_e32 v0, 0xffff0000, v0
	v_add_f32_e32 v8, v8, v9
	v_lshlrev_b32_e32 v10, 16, v1
	v_add_f32_e32 v0, v8, v0
	v_and_b32_e32 v1, 0xffff0000, v1
	v_add_f32_e32 v0, v0, v10
	v_lshlrev_b32_e32 v11, 16, v2
	v_add_f32_e32 v0, v0, v1
	v_and_b32_e32 v2, 0xffff0000, v2
	v_add_f32_e32 v0, v0, v11
	v_lshlrev_b32_e32 v12, 16, v3
	v_add_f32_e32 v0, v0, v2
	v_and_b32_e32 v3, 0xffff0000, v3
	v_add_f32_e32 v0, v0, v12
	v_add_f32_e32 v0, v0, v3
	s_waitcnt lgkmcnt(0)
	v_lshlrev_b32_e32 v1, 16, v4
	v_and_b32_e32 v2, 0xffff0000, v4
	v_add_f32_e32 v0, v0, v1
	v_lshlrev_b32_e32 v3, 16, v5
	v_add_f32_e32 v0, v0, v2
	v_and_b32_e32 v4, 0xffff0000, v5
	v_add_f32_e32 v0, v0, v3
	v_lshlrev_b32_e32 v5, 16, v6
	v_add_f32_e32 v0, v0, v4
	v_add_f32_e32 v4, v0, v5
	ds_read_b128 v[0:3], v16 offset:224
	v_and_b32_e32 v6, 0xffff0000, v6
	v_lshlrev_b32_e32 v8, 16, v7
	v_add_f32_e32 v4, v4, v6
	v_and_b32_e32 v7, 0xffff0000, v7
	v_add_f32_e32 v4, v4, v8
	v_add_f32_e32 v8, v4, v7
	ds_read_b128 v[4:7], v16 offset:240
	s_waitcnt lgkmcnt(1)
	v_lshlrev_b32_e32 v9, 16, v0
	v_and_b32_e32 v0, 0xffff0000, v0
	v_add_f32_e32 v8, v8, v9
	v_lshlrev_b32_e32 v10, 16, v1
	v_add_f32_e32 v0, v8, v0
	v_and_b32_e32 v1, 0xffff0000, v1
	v_add_f32_e32 v0, v0, v10
	v_lshlrev_b32_e32 v11, 16, v2
	v_add_f32_e32 v0, v0, v1
	v_and_b32_e32 v2, 0xffff0000, v2
	v_add_f32_e32 v0, v0, v11
	v_lshlrev_b32_e32 v12, 16, v3
	v_add_f32_e32 v0, v0, v2
	v_and_b32_e32 v3, 0xffff0000, v3
	v_add_f32_e32 v0, v0, v12
	v_add_f32_e32 v0, v0, v3
	s_waitcnt lgkmcnt(0)
	v_lshlrev_b32_e32 v1, 16, v4
	v_and_b32_e32 v2, 0xffff0000, v4
	v_add_f32_e32 v0, v0, v1
	v_lshlrev_b32_e32 v3, 16, v5
	v_add_f32_e32 v0, v0, v2
	v_and_b32_e32 v4, 0xffff0000, v5
	v_add_f32_e32 v0, v0, v3
	v_lshlrev_b32_e32 v5, 16, v6
	v_add_f32_e32 v0, v0, v4
	v_and_b32_e32 v6, 0xffff0000, v6
	v_add_f32_e32 v0, v0, v5
	v_lshlrev_b32_e32 v8, 16, v7
	v_add_f32_e32 v0, v0, v6
	v_and_b32_e32 v7, 0xffff0000, v7
	v_add_f32_e32 v0, v0, v8
	v_lshlrev_b32_e32 v2, 1, v210
	v_add_f32_e32 v3, v0, v7
	v_add3_u32 v0, s36, 4, v2
	v_lshl_or_b32 v4, v0, 3, s37
	v_mov_b32_e32 v0, s0
	v_mov_b32_e32 v1, s35
	v_cndmask_b32_e32 v0, v0, v1, vcc
	v_ashrrev_i32_e32 v1, 31, v0
	v_mad_i64_i32 v[0:1], s[0:1], v4, s90, v[0:1]
	v_lshlrev_b64 v[4:5], 8, v[0:1]
	v_lshl_add_u64 v[4:5], s[22:23], 0, v[4:5]
	v_lshlrev_b32_e32 v160, 2, v208
	v_lshl_add_u64 v[4:5], v[4:5], 0, v[160:161]
	v_cmp_eq_u32_e32 vcc, 0, v208
	global_store_dword v[4:5], v3, off
	s_and_b64 exec, exec, vcc
	s_cbranch_execz .LBB0_958
	v_lshl_add_u32 v2, v2, 2, s33
	ds_read_b64 v[2:3], v2 offset:53248
	v_lshl_add_u64 v[0:1], v[0:1], 3, s[24:25]
	s_waitcnt lgkmcnt(0)
	v_add_f32_e32 v4, v2, v3
	v_mov_b32_e32 v5, v2
	global_store_dwordx2 v[0:1], v[4:5], off
	s_branch .LBB0_958

.LBB0_1296:
	s_or_b64 exec, exec, s[14:15]
	s_ashr_i32 s0, s0, 24
	v_mov_b32_e32 v250, v244
	v_mov_b32_e32 v251, v245
	v_add_u32_e32 v128, s6, v143
	s_cmp_gt_i32 s0, 15
	s_cbranch_scc1 .Lp0_gate
	v_lshlrev_b32_e32 v129, 6, v141
	v_lshl_or_b32 v129, v142, 4, v129
	s_lshl_b32 s1, s4, 1
	v_add_u32_e32 v129, s1, v129
	v_lshl_add_u32 v130, v128, 13, v129
	v_mov_b32_e32 v131, v130
	v_cvt_pk_bf16_f32 v132, v124, v125
	v_cvt_pk_bf16_f32 v133, v126, v127
	v_cvt_pk_bf16_f32 v134, v120, v121
	v_cvt_pk_bf16_f32 v135, v122, v123
	s_nop 1
	v_permlane32_swap_b32_e32 v132, v134
	v_permlane32_swap_b32_e32 v133, v135
	s_nop 1
	v_permlane16_swap_b32_e32 v132, v134
	v_permlane16_swap_b32_e32 v133, v135
	global_store_dwordx4 v131, v[132:135], s[58:59]
	v_cvt_pk_bf16_f32 v136, v116, v117
	v_cvt_pk_bf16_f32 v137, v118, v119
	v_cvt_pk_bf16_f32 v138, v112, v113
	v_cvt_pk_bf16_f32 v139, v114, v115
	s_nop 1
	v_permlane32_swap_b32_e32 v136, v138
	v_permlane32_swap_b32_e32 v137, v139
	s_nop 1
	v_permlane16_swap_b32_e32 v136, v138
	v_permlane16_swap_b32_e32 v137, v139
	global_store_dwordx4 v131, v[136:139], s[58:59] offset:256
	v_add_u32_e32 v131, 0x20000, v130
	v_cvt_pk_bf16_f32 v132, v108, v109
	v_cvt_pk_bf16_f32 v133, v110, v111
	v_cvt_pk_bf16_f32 v134, v104, v105
	v_cvt_pk_bf16_f32 v135, v106, v107
	s_nop 1
	v_permlane32_swap_b32_e32 v132, v134
	v_permlane32_swap_b32_e32 v133, v135
	s_nop 1
	v_permlane16_swap_b32_e32 v132, v134
	v_permlane16_swap_b32_e32 v133, v135
	global_store_dwordx4 v131, v[132:135], s[58:59]
	v_cvt_pk_bf16_f32 v136, v100, v101
	v_cvt_pk_bf16_f32 v137, v102, v103
	v_cvt_pk_bf16_f32 v138, v96, v97
	v_cvt_pk_bf16_f32 v139, v98, v99
	s_nop 1
	v_permlane32_swap_b32_e32 v136, v138
	v_permlane32_swap_b32_e32 v137, v139
	s_nop 1
	v_permlane16_swap_b32_e32 v136, v138
	v_permlane16_swap_b32_e32 v137, v139
	global_store_dwordx4 v131, v[136:139], s[58:59] offset:256
	v_add_u32_e32 v131, 0x40000, v130
	v_cvt_pk_bf16_f32 v132, v92, v93
	v_cvt_pk_bf16_f32 v133, v94, v95
	v_cvt_pk_bf16_f32 v134, v88, v89
	v_cvt_pk_bf16_f32 v135, v90, v91
	s_nop 1
	v_permlane32_swap_b32_e32 v132, v134
	v_permlane32_swap_b32_e32 v133, v135
	s_nop 1
	v_permlane16_swap_b32_e32 v132, v134
	v_permlane16_swap_b32_e32 v133, v135
	global_store_dwordx4 v131, v[132:135], s[58:59]
	v_cvt_pk_bf16_f32 v136, v84, v85
	v_cvt_pk_bf16_f32 v137, v86, v87
	v_cvt_pk_bf16_f32 v138, v80, v81
	v_cvt_pk_bf16_f32 v139, v82, v83
	s_nop 1
	v_permlane32_swap_b32_e32 v136, v138
	v_permlane32_swap_b32_e32 v137, v139
	s_nop 1
	v_permlane16_swap_b32_e32 v136, v138
	v_permlane16_swap_b32_e32 v137, v139
	global_store_dwordx4 v131, v[136:139], s[58:59] offset:256
	v_add_u32_e32 v131, 0x60000, v130
	v_cvt_pk_bf16_f32 v132, v76, v77
	v_cvt_pk_bf16_f32 v133, v78, v79
	v_cvt_pk_bf16_f32 v134, v72, v73
	v_cvt_pk_bf16_f32 v135, v74, v75
	s_nop 1
	v_permlane32_swap_b32_e32 v132, v134
	v_permlane32_swap_b32_e32 v133, v135
	s_nop 1
	v_permlane16_swap_b32_e32 v132, v134
	v_permlane16_swap_b32_e32 v133, v135
	global_store_dwordx4 v131, v[132:135], s[58:59]
	v_cvt_pk_bf16_f32 v136, v68, v69
	v_cvt_pk_bf16_f32 v137, v70, v71
	v_cvt_pk_bf16_f32 v138, v64, v65
	v_cvt_pk_bf16_f32 v139, v66, v67
	s_nop 1
	v_permlane32_swap_b32_e32 v136, v138
	v_permlane32_swap_b32_e32 v137, v139
	s_nop 1
	v_permlane16_swap_b32_e32 v136, v138
	v_permlane16_swap_b32_e32 v137, v139
	global_store_dwordx4 v131, v[136:139], s[58:59] offset:256
	v_add_u32_e32 v131, 0x100000, v130
	v_cvt_pk_bf16_f32 v132, v60, v61
	v_cvt_pk_bf16_f32 v133, v62, v63
	v_cvt_pk_bf16_f32 v134, v56, v57
	v_cvt_pk_bf16_f32 v135, v58, v59
	s_nop 1
	v_permlane32_swap_b32_e32 v132, v134
	v_permlane32_swap_b32_e32 v133, v135
	s_nop 1
	v_permlane16_swap_b32_e32 v132, v134
	v_permlane16_swap_b32_e32 v133, v135
	global_store_dwordx4 v131, v[132:135], s[58:59]
	v_cvt_pk_bf16_f32 v136, v52, v53
	v_cvt_pk_bf16_f32 v137, v54, v55
	v_cvt_pk_bf16_f32 v138, v48, v49
	v_cvt_pk_bf16_f32 v139, v50, v51
	s_nop 1
	v_permlane32_swap_b32_e32 v136, v138
	v_permlane32_swap_b32_e32 v137, v139
	s_nop 1
	v_permlane16_swap_b32_e32 v136, v138
	v_permlane16_swap_b32_e32 v137, v139
	global_store_dwordx4 v131, v[136:139], s[58:59] offset:256
	v_add_u32_e32 v131, 0x120000, v130
	v_cvt_pk_bf16_f32 v132, v44, v45
	v_cvt_pk_bf16_f32 v133, v46, v47
	v_cvt_pk_bf16_f32 v134, v40, v41
	v_cvt_pk_bf16_f32 v135, v42, v43
	s_nop 1
	v_permlane32_swap_b32_e32 v132, v134
	v_permlane32_swap_b32_e32 v133, v135
	s_nop 1
	v_permlane16_swap_b32_e32 v132, v134
	v_permlane16_swap_b32_e32 v133, v135
	global_store_dwordx4 v131, v[132:135], s[58:59]
	v_cvt_pk_bf16_f32 v136, v36, v37
	v_cvt_pk_bf16_f32 v137, v38, v39
	v_cvt_pk_bf16_f32 v138, v32, v33
	v_cvt_pk_bf16_f32 v139, v34, v35
	s_nop 1
	v_permlane32_swap_b32_e32 v136, v138
	v_permlane32_swap_b32_e32 v137, v139
	s_nop 1
	v_permlane16_swap_b32_e32 v136, v138
	v_permlane16_swap_b32_e32 v137, v139
	global_store_dwordx4 v131, v[136:139], s[58:59] offset:256
	v_add_u32_e32 v131, 0x140000, v130
	v_cvt_pk_bf16_f32 v132, v28, v29
	v_cvt_pk_bf16_f32 v133, v30, v31
	v_cvt_pk_bf16_f32 v134, v24, v25
	v_cvt_pk_bf16_f32 v135, v26, v27
	s_nop 1
	v_permlane32_swap_b32_e32 v132, v134
	v_permlane32_swap_b32_e32 v133, v135
	s_nop 1
	v_permlane16_swap_b32_e32 v132, v134
	v_permlane16_swap_b32_e32 v133, v135
	global_store_dwordx4 v131, v[132:135], s[58:59]
	v_cvt_pk_bf16_f32 v136, v20, v21
	v_cvt_pk_bf16_f32 v137, v22, v23
	v_cvt_pk_bf16_f32 v138, v16, v17
	v_cvt_pk_bf16_f32 v139, v18, v19
	s_nop 1
	v_permlane32_swap_b32_e32 v136, v138
	v_permlane32_swap_b32_e32 v137, v139
	s_nop 1
	v_permlane16_swap_b32_e32 v136, v138
	v_permlane16_swap_b32_e32 v137, v139
	global_store_dwordx4 v131, v[136:139], s[58:59] offset:256
	v_add_u32_e32 v131, 0x160000, v130
	v_cvt_pk_bf16_f32 v132, v12, v13
	v_cvt_pk_bf16_f32 v133, v14, v15
	v_cvt_pk_bf16_f32 v134, v8, v9
	v_cvt_pk_bf16_f32 v135, v10, v11
	s_nop 1
	v_permlane32_swap_b32_e32 v132, v134
	v_permlane32_swap_b32_e32 v133, v135
	s_nop 1
	v_permlane16_swap_b32_e32 v132, v134
	v_permlane16_swap_b32_e32 v133, v135
	global_store_dwordx4 v131, v[132:135], s[58:59]
	v_cvt_pk_bf16_f32 v136, v4, v5
	v_cvt_pk_bf16_f32 v137, v6, v7
	v_cvt_pk_bf16_f32 v138, v0, v1
	v_cvt_pk_bf16_f32 v139, v2, v3
	s_nop 1
	v_permlane32_swap_b32_e32 v136, v138
	v_permlane32_swap_b32_e32 v137, v139
	s_nop 1
	v_permlane16_swap_b32_e32 v136, v138
	v_permlane16_swap_b32_e32 v137, v139
	global_store_dwordx4 v131, v[136:139], s[58:59] offset:256
	s_branch .LBB0_1285
.Lp0_gate:
	v_cmp_eq_u32_e32 vcc, 0, v141
	s_and_saveexec_b64 s[2:3], vcc
	s_cbranch_execz .Lp0_gate_done
	v_lshlrev_b32_e32 v129, 4, v142
	global_load_dwordx4 v[144:147], v129, s[8:9]
	global_load_dwordx4 v[148:151], v129, s[8:9] offset:64
	v_lshl_add_u32 v130, v128, 7, v129
	s_waitcnt vmcnt(0)
	v_mov_b32_e32 v131, v130
	v_pk_add_f32 v[152:153], v[124:125], v[144:145]
	v_pk_add_f32 v[154:155], v[126:127], v[146:147]
	global_store_dwordx4 v131, v[152:155], s[10:11]
	v_pk_add_f32 v[156:157], v[120:121], v[148:149]
	v_pk_add_f32 v[158:159], v[122:123], v[150:151]
	global_store_dwordx4 v131, v[156:159], s[10:11] offset:64
	v_add_u32_e32 v131, 0x800, v130
	v_pk_add_f32 v[152:153], v[108:109], v[144:145]
	v_pk_add_f32 v[154:155], v[110:111], v[146:147]
	global_store_dwordx4 v131, v[152:155], s[10:11]
	v_pk_add_f32 v[156:157], v[104:105], v[148:149]
	v_pk_add_f32 v[158:159], v[106:107], v[150:151]
	global_store_dwordx4 v131, v[156:159], s[10:11] offset:64
	v_add_u32_e32 v131, 0x1000, v130
	v_pk_add_f32 v[152:153], v[92:93], v[144:145]
	v_pk_add_f32 v[154:155], v[94:95], v[146:147]
	global_store_dwordx4 v131, v[152:155], s[10:11]
	v_pk_add_f32 v[156:157], v[88:89], v[148:149]
	v_pk_add_f32 v[158:159], v[90:91], v[150:151]
	global_store_dwordx4 v131, v[156:159], s[10:11] offset:64
	v_add_u32_e32 v131, 0x1800, v130
	v_pk_add_f32 v[152:153], v[76:77], v[144:145]
	v_pk_add_f32 v[154:155], v[78:79], v[146:147]
	global_store_dwordx4 v131, v[152:155], s[10:11]
	v_pk_add_f32 v[156:157], v[72:73], v[148:149]
	v_pk_add_f32 v[158:159], v[74:75], v[150:151]
	global_store_dwordx4 v131, v[156:159], s[10:11] offset:64
	v_add_u32_e32 v131, 0x4000, v130
	v_pk_add_f32 v[152:153], v[60:61], v[144:145]
	v_pk_add_f32 v[154:155], v[62:63], v[146:147]
	global_store_dwordx4 v131, v[152:155], s[10:11]
	v_pk_add_f32 v[156:157], v[56:57], v[148:149]
	v_pk_add_f32 v[158:159], v[58:59], v[150:151]
	global_store_dwordx4 v131, v[156:159], s[10:11] offset:64
	v_add_u32_e32 v131, 0x4800, v130
	v_pk_add_f32 v[152:153], v[44:45], v[144:145]
	v_pk_add_f32 v[154:155], v[46:47], v[146:147]
	global_store_dwordx4 v131, v[152:155], s[10:11]
	v_pk_add_f32 v[156:157], v[40:41], v[148:149]
	v_pk_add_f32 v[158:159], v[42:43], v[150:151]
	global_store_dwordx4 v131, v[156:159], s[10:11] offset:64
	v_add_u32_e32 v131, 0x5000, v130
	v_pk_add_f32 v[152:153], v[28:29], v[144:145]
	v_pk_add_f32 v[154:155], v[30:31], v[146:147]
	global_store_dwordx4 v131, v[152:155], s[10:11]
	v_pk_add_f32 v[156:157], v[24:25], v[148:149]
	v_pk_add_f32 v[158:159], v[26:27], v[150:151]
	global_store_dwordx4 v131, v[156:159], s[10:11] offset:64
	v_add_u32_e32 v131, 0x5800, v130
	v_pk_add_f32 v[152:153], v[12:13], v[144:145]
	v_pk_add_f32 v[154:155], v[14:15], v[146:147]
	global_store_dwordx4 v131, v[152:155], s[10:11]
	v_pk_add_f32 v[156:157], v[8:9], v[148:149]
	v_pk_add_f32 v[158:159], v[10:11], v[150:151]
	global_store_dwordx4 v131, v[156:159], s[10:11] offset:64
.Lp0_gate_done:
	s_or_b64 exec, exec, s[2:3]
	s_branch .LBB0_1285
